# attention: waves 4-7 take each half-step barrier before the trailing VALU block (half stagger); gla_scan hand-pipelined; gla_out mask+load batching
# speedup vs baseline: 1.0145x; 1.0127x over previous
.LBB0_1057:
	s_add_u32 s14, s6, 0x42300000
	s_addc_u32 s15, s7, 0
	s_add_u32 s16, s6, 0x46300000
	s_addc_u32 s17, s7, 0
	s_add_u32 s18, s6, 0x42200000
	s_addc_u32 s19, s7, 0
	global_load_dword v27, v2, s[14:15]
	global_load_dwordx2 v[134:135], v4, s[18:19]
	s_add_u32 s14, s14, 0x40000
	s_addc_u32 s15, s15, 0
	s_add_u32 s18, s18, 0x800
	s_addc_u32 s19, s19, 0
	global_load_dword v28, v2, s[14:15]
	global_load_dwordx2 v[136:137], v4, s[18:19]
	s_add_u32 s14, s14, 0x40000
	s_addc_u32 s15, s15, 0
	s_add_u32 s18, s18, 0x800
	s_addc_u32 s19, s19, 0
	global_load_dword v29, v2, s[14:15]
	global_load_dwordx2 v[138:139], v4, s[18:19]
	s_add_u32 s14, s14, 0x40000
	s_addc_u32 s15, s15, 0
	s_add_u32 s18, s18, 0x800
	s_addc_u32 s19, s19, 0
	global_load_dword v30, v2, s[14:15]
	global_load_dwordx2 v[140:141], v4, s[18:19]
	s_add_u32 s14, s14, 0x40000
	s_addc_u32 s15, s15, 0
	s_add_u32 s18, s18, 0x800
	s_addc_u32 s19, s19, 0
	global_load_dword v31, v2, s[14:15]
	global_load_dwordx2 v[142:143], v4, s[18:19]
	s_add_u32 s14, s14, 0x40000
	s_addc_u32 s15, s15, 0
	s_add_u32 s18, s18, 0x800
	s_addc_u32 s19, s19, 0
	global_load_dword v32, v2, s[14:15]
	global_load_dwordx2 v[144:145], v4, s[18:19]
	s_add_u32 s14, s14, 0x40000
	s_addc_u32 s15, s15, 0
	s_add_u32 s18, s18, 0x800
	s_addc_u32 s19, s19, 0
	global_load_dword v33, v2, s[14:15]
	global_load_dwordx2 v[146:147], v4, s[18:19]
	s_add_u32 s14, s14, 0x40000
	s_addc_u32 s15, s15, 0
	s_add_u32 s18, s18, 0x800
	s_addc_u32 s19, s19, 0
	global_load_dword v34, v2, s[14:15]
	global_load_dwordx2 v[148:149], v4, s[18:19]
	s_add_u32 s14, s14, 0x40000
	s_addc_u32 s15, s15, 0
	s_add_u32 s18, s18, 0x800
	s_addc_u32 s19, s19, 0
	global_load_dword v35, v2, s[14:15]
	global_load_dwordx2 v[150:151], v4, s[18:19]
	s_add_u32 s14, s14, 0x40000
	s_addc_u32 s15, s15, 0
	s_add_u32 s18, s18, 0x800
	s_addc_u32 s19, s19, 0
	global_load_dword v36, v2, s[14:15]
	global_load_dwordx2 v[152:153], v4, s[18:19]
	s_add_u32 s14, s14, 0x40000
	s_addc_u32 s15, s15, 0
	s_add_u32 s18, s18, 0x800
	s_addc_u32 s19, s19, 0
	global_load_dword v37, v2, s[14:15]
	global_load_dwordx2 v[154:155], v4, s[18:19]
	s_add_u32 s14, s14, 0x40000
	s_addc_u32 s15, s15, 0
	s_add_u32 s18, s18, 0x800
	s_addc_u32 s19, s19, 0
	global_load_dword v38, v2, s[14:15]
	global_load_dwordx2 v[170:171], v4, s[18:19]
	s_add_u32 s14, s14, 0x40000
	s_addc_u32 s15, s15, 0
	s_add_u32 s18, s18, 0x800
	s_addc_u32 s19, s19, 0
	global_load_dword v39, v2, s[14:15]
	global_load_dwordx2 v[172:173], v4, s[18:19]
	s_add_u32 s14, s14, 0x40000
	s_addc_u32 s15, s15, 0
	s_add_u32 s18, s18, 0x800
	s_addc_u32 s19, s19, 0
	global_load_dword v40, v2, s[14:15]
	global_load_dwordx2 v[174:175], v4, s[18:19]
	s_add_u32 s14, s14, 0x40000
	s_addc_u32 s15, s15, 0
	s_add_u32 s18, s18, 0x800
	s_addc_u32 s19, s19, 0
	global_load_dword v41, v2, s[14:15]
	global_load_dwordx2 v[176:177], v4, s[18:19]
	s_add_u32 s14, s14, 0x40000
	s_addc_u32 s15, s15, 0
	s_add_u32 s18, s18, 0x800
	s_addc_u32 s19, s19, 0
	global_load_dword v42, v2, s[14:15]
	global_load_dwordx2 v[178:179], v4, s[18:19]
	s_add_u32 s14, s14, 0x40000
	s_addc_u32 s15, s15, 0
	s_add_u32 s18, s18, 0x800
	s_addc_u32 s19, s19, 0
	global_load_dword v43, v2, s[14:15]
	global_load_dwordx2 v[180:181], v4, s[18:19]
	s_add_u32 s14, s14, 0x40000
	s_addc_u32 s15, s15, 0
	s_add_u32 s18, s18, 0x800
	s_addc_u32 s19, s19, 0
	global_load_dword v44, v2, s[14:15]
	global_load_dwordx2 v[182:183], v4, s[18:19]
	s_add_u32 s14, s14, 0x40000
	s_addc_u32 s15, s15, 0
	s_add_u32 s18, s18, 0x800
	s_addc_u32 s19, s19, 0
	global_load_dword v45, v2, s[14:15]
	global_load_dwordx2 v[188:189], v4, s[18:19]
	s_add_u32 s14, s14, 0x40000
	s_addc_u32 s15, s15, 0
	s_add_u32 s18, s18, 0x800
	s_addc_u32 s19, s19, 0
	global_load_dword v46, v2, s[14:15]
	global_load_dwordx2 v[190:191], v4, s[18:19]
	s_add_u32 s14, s14, 0x40000
	s_addc_u32 s15, s15, 0
	s_add_u32 s18, s18, 0x800
	s_addc_u32 s19, s19, 0
	global_load_dword v50, v2, s[14:15]
	global_load_dwordx2 v[192:193], v4, s[18:19]
	s_add_u32 s14, s14, 0x40000
	s_addc_u32 s15, s15, 0
	s_add_u32 s18, s18, 0x800
	s_addc_u32 s19, s19, 0
	global_load_dword v51, v2, s[14:15]
	global_load_dwordx2 v[194:195], v4, s[18:19]
	s_add_u32 s14, s14, 0x40000
	s_addc_u32 s15, s15, 0
	s_add_u32 s18, s18, 0x800
	s_addc_u32 s19, s19, 0
	global_load_dword v52, v2, s[14:15]
	global_load_dwordx2 v[196:197], v4, s[18:19]
	s_add_u32 s14, s14, 0x40000
	s_addc_u32 s15, s15, 0
	s_add_u32 s18, s18, 0x800
	s_addc_u32 s19, s19, 0
	global_load_dword v53, v2, s[14:15]
	global_load_dwordx2 v[198:199], v4, s[18:19]
	s_add_u32 s14, s14, 0x40000
	s_addc_u32 s15, s15, 0
	s_add_u32 s18, s18, 0x800
	s_addc_u32 s19, s19, 0
	global_load_dword v54, v2, s[14:15]
	global_load_dwordx2 v[202:203], v4, s[18:19]
	s_add_u32 s14, s14, 0x40000
	s_addc_u32 s15, s15, 0
	s_add_u32 s18, s18, 0x800
	s_addc_u32 s19, s19, 0
	global_load_dword v55, v2, s[14:15]
	global_load_dwordx2 v[204:205], v4, s[18:19]
	s_add_u32 s14, s14, 0x40000
	s_addc_u32 s15, s15, 0
	s_add_u32 s18, s18, 0x800
	s_addc_u32 s19, s19, 0
	global_load_dword v56, v2, s[14:15]
	global_load_dwordx2 v[206:207], v4, s[18:19]
	s_add_u32 s14, s14, 0x40000
	s_addc_u32 s15, s15, 0
	s_add_u32 s18, s18, 0x800
	s_addc_u32 s19, s19, 0
	global_load_dword v57, v2, s[14:15]
	global_load_dwordx2 v[208:209], v4, s[18:19]
	s_add_u32 s14, s14, 0x40000
	s_addc_u32 s15, s15, 0
	s_add_u32 s18, s18, 0x800
	s_addc_u32 s19, s19, 0
	global_load_dword v58, v2, s[14:15]
	global_load_dwordx2 v[210:211], v4, s[18:19]
	s_add_u32 s14, s14, 0x40000
	s_addc_u32 s15, s15, 0
	s_add_u32 s18, s18, 0x800
	s_addc_u32 s19, s19, 0
	global_load_dword v59, v2, s[14:15]
	global_load_dwordx2 v[212:213], v4, s[18:19]
	s_add_u32 s14, s14, 0x40000
	s_addc_u32 s15, s15, 0
	s_add_u32 s18, s18, 0x800
	s_addc_u32 s19, s19, 0
	global_load_dword v60, v2, s[14:15]
	global_load_dwordx2 v[214:215], v4, s[18:19]
	s_add_u32 s14, s14, 0x40000
	s_addc_u32 s15, s15, 0
	s_add_u32 s18, s18, 0x800
	s_addc_u32 s19, s19, 0
	global_load_dword v61, v2, s[14:15]
	global_load_dwordx2 v[216:217], v4, s[18:19]
	s_add_u32 s14, s14, 0x40000
	s_addc_u32 s15, s15, 0
	s_add_u32 s18, s18, 0x800
	s_addc_u32 s19, s19, 0
	s_waitcnt vmcnt(62)
	v_lshlrev_b32_e32 v16, 16, v27
	v_and_b32_e32 v17, 0xffff0000, v27
	v_mov_b32_e32 v14, 0
	v_mov_b32_e32 v15, 0
	v_pk_add_f32 v[10:11], v[14:15], v[16:17]
	v_cvt_pk_bf16_f32 v18, v14, v15
	v_mul_f32_e32 v12, 0x3fb8aa3b, v134
	v_mul_f32_e32 v13, 0x3fb8aa3b, v135
	global_store_dword v2, v18, s[16:17]
	s_add_u32 s16, s16, 0x40000
	s_addc_u32 s17, s17, 0
	v_exp_f32_e32 v12, v12
	v_exp_f32_e32 v13, v13
	global_load_dword v27, v2, s[14:15]
	global_load_dwordx2 v[134:135], v4, s[18:19]
	s_add_u32 s14, s14, 0x40000
	s_addc_u32 s15, s15, 0
	s_add_u32 s18, s18, 0x800
	s_addc_u32 s19, s19, 0
	s_waitcnt vmcnt(63)
	v_lshlrev_b32_e32 v16, 16, v28
	v_and_b32_e32 v17, 0xffff0000, v28
	v_pk_mul_f32 v[14:15], v[10:11], v[12:13]
	v_pk_fma_f32 v[10:11], v[10:11], v[12:13], v[16:17]
	v_cvt_pk_bf16_f32 v19, v14, v15
	v_mul_f32_e32 v12, 0x3fb8aa3b, v136
	v_mul_f32_e32 v13, 0x3fb8aa3b, v137
	global_store_dword v2, v19, s[16:17]
	s_add_u32 s16, s16, 0x40000
	s_addc_u32 s17, s17, 0
	v_exp_f32_e32 v12, v12
	v_exp_f32_e32 v13, v13
	global_load_dword v28, v2, s[14:15]
	global_load_dwordx2 v[136:137], v4, s[18:19]
	s_add_u32 s14, s14, 0x40000
	s_addc_u32 s15, s15, 0
	s_add_u32 s18, s18, 0x800
	s_addc_u32 s19, s19, 0
	s_waitcnt vmcnt(63)
	v_lshlrev_b32_e32 v16, 16, v29
	v_and_b32_e32 v17, 0xffff0000, v29
	v_pk_mul_f32 v[14:15], v[10:11], v[12:13]
	v_pk_fma_f32 v[10:11], v[10:11], v[12:13], v[16:17]
	v_cvt_pk_bf16_f32 v22, v14, v15
	v_mul_f32_e32 v12, 0x3fb8aa3b, v138
	v_mul_f32_e32 v13, 0x3fb8aa3b, v139
	global_store_dword v2, v22, s[16:17]
	s_add_u32 s16, s16, 0x40000
	s_addc_u32 s17, s17, 0
	v_exp_f32_e32 v12, v12
	v_exp_f32_e32 v13, v13
	global_load_dword v29, v2, s[14:15]
	global_load_dwordx2 v[138:139], v4, s[18:19]
	s_add_u32 s14, s14, 0x40000
	s_addc_u32 s15, s15, 0
	s_add_u32 s18, s18, 0x800
	s_addc_u32 s19, s19, 0
	s_waitcnt vmcnt(63)
	v_lshlrev_b32_e32 v16, 16, v30
	v_and_b32_e32 v17, 0xffff0000, v30
	v_pk_mul_f32 v[14:15], v[10:11], v[12:13]
	v_pk_fma_f32 v[10:11], v[10:11], v[12:13], v[16:17]
	v_cvt_pk_bf16_f32 v18, v14, v15
	v_mul_f32_e32 v12, 0x3fb8aa3b, v140
	v_mul_f32_e32 v13, 0x3fb8aa3b, v141
	global_store_dword v2, v18, s[16:17]
	s_add_u32 s16, s16, 0x40000
	s_addc_u32 s17, s17, 0
	v_exp_f32_e32 v12, v12
	v_exp_f32_e32 v13, v13
	global_load_dword v30, v2, s[14:15]
	global_load_dwordx2 v[140:141], v4, s[18:19]
	s_add_u32 s14, s14, 0x40000
	s_addc_u32 s15, s15, 0
	s_add_u32 s18, s18, 0x800
	s_addc_u32 s19, s19, 0
	s_waitcnt vmcnt(63)
	v_lshlrev_b32_e32 v16, 16, v31
	v_and_b32_e32 v17, 0xffff0000, v31
	v_pk_mul_f32 v[14:15], v[10:11], v[12:13]
	v_pk_fma_f32 v[10:11], v[10:11], v[12:13], v[16:17]
	v_cvt_pk_bf16_f32 v19, v14, v15
	v_mul_f32_e32 v12, 0x3fb8aa3b, v142
	v_mul_f32_e32 v13, 0x3fb8aa3b, v143
	global_store_dword v2, v19, s[16:17]
	s_add_u32 s16, s16, 0x40000
	s_addc_u32 s17, s17, 0
	v_exp_f32_e32 v12, v12
	v_exp_f32_e32 v13, v13
	global_load_dword v31, v2, s[14:15]
	global_load_dwordx2 v[142:143], v4, s[18:19]
	s_add_u32 s14, s14, 0x40000
	s_addc_u32 s15, s15, 0
	s_add_u32 s18, s18, 0x800
	s_addc_u32 s19, s19, 0
	s_waitcnt vmcnt(63)
	v_lshlrev_b32_e32 v16, 16, v32
	v_and_b32_e32 v17, 0xffff0000, v32
	v_pk_mul_f32 v[14:15], v[10:11], v[12:13]
	v_pk_fma_f32 v[10:11], v[10:11], v[12:13], v[16:17]
	v_cvt_pk_bf16_f32 v22, v14, v15
	v_mul_f32_e32 v12, 0x3fb8aa3b, v144
	v_mul_f32_e32 v13, 0x3fb8aa3b, v145
	global_store_dword v2, v22, s[16:17]
	s_add_u32 s16, s16, 0x40000
	s_addc_u32 s17, s17, 0
	v_exp_f32_e32 v12, v12
	v_exp_f32_e32 v13, v13
	global_load_dword v32, v2, s[14:15]
	global_load_dwordx2 v[144:145], v4, s[18:19]
	s_add_u32 s14, s14, 0x40000
	s_addc_u32 s15, s15, 0
	s_add_u32 s18, s18, 0x800
	s_addc_u32 s19, s19, 0
	s_waitcnt vmcnt(63)
	v_lshlrev_b32_e32 v16, 16, v33
	v_and_b32_e32 v17, 0xffff0000, v33
	v_pk_mul_f32 v[14:15], v[10:11], v[12:13]
	v_pk_fma_f32 v[10:11], v[10:11], v[12:13], v[16:17]
	v_cvt_pk_bf16_f32 v18, v14, v15
	v_mul_f32_e32 v12, 0x3fb8aa3b, v146
	v_mul_f32_e32 v13, 0x3fb8aa3b, v147
	global_store_dword v2, v18, s[16:17]
	s_add_u32 s16, s16, 0x40000
	s_addc_u32 s17, s17, 0
	v_exp_f32_e32 v12, v12
	v_exp_f32_e32 v13, v13
	global_load_dword v33, v2, s[14:15]
	global_load_dwordx2 v[146:147], v4, s[18:19]
	s_add_u32 s14, s14, 0x40000
	s_addc_u32 s15, s15, 0
	s_add_u32 s18, s18, 0x800
	s_addc_u32 s19, s19, 0
	s_waitcnt vmcnt(63)
	v_lshlrev_b32_e32 v16, 16, v34
	v_and_b32_e32 v17, 0xffff0000, v34
	v_pk_mul_f32 v[14:15], v[10:11], v[12:13]
	v_pk_fma_f32 v[10:11], v[10:11], v[12:13], v[16:17]
	v_cvt_pk_bf16_f32 v19, v14, v15
	v_mul_f32_e32 v12, 0x3fb8aa3b, v148
	v_mul_f32_e32 v13, 0x3fb8aa3b, v149
	global_store_dword v2, v19, s[16:17]
	s_add_u32 s16, s16, 0x40000
	s_addc_u32 s17, s17, 0
	v_exp_f32_e32 v12, v12
	v_exp_f32_e32 v13, v13
	global_load_dword v34, v2, s[14:15]
	global_load_dwordx2 v[148:149], v4, s[18:19]
	s_add_u32 s14, s14, 0x40000
	s_addc_u32 s15, s15, 0
	s_add_u32 s18, s18, 0x800
	s_addc_u32 s19, s19, 0
	s_waitcnt vmcnt(63)
	v_lshlrev_b32_e32 v16, 16, v35
	v_and_b32_e32 v17, 0xffff0000, v35
	v_pk_mul_f32 v[14:15], v[10:11], v[12:13]
	v_pk_fma_f32 v[10:11], v[10:11], v[12:13], v[16:17]
	v_cvt_pk_bf16_f32 v22, v14, v15
	v_mul_f32_e32 v12, 0x3fb8aa3b, v150
	v_mul_f32_e32 v13, 0x3fb8aa3b, v151
	global_store_dword v2, v22, s[16:17]
	s_add_u32 s16, s16, 0x40000
	s_addc_u32 s17, s17, 0
	v_exp_f32_e32 v12, v12
	v_exp_f32_e32 v13, v13
	global_load_dword v35, v2, s[14:15]
	global_load_dwordx2 v[150:151], v4, s[18:19]
	s_add_u32 s14, s14, 0x40000
	s_addc_u32 s15, s15, 0
	s_add_u32 s18, s18, 0x800
	s_addc_u32 s19, s19, 0
	s_waitcnt vmcnt(63)
	v_lshlrev_b32_e32 v16, 16, v36
	v_and_b32_e32 v17, 0xffff0000, v36
	v_pk_mul_f32 v[14:15], v[10:11], v[12:13]
	v_pk_fma_f32 v[10:11], v[10:11], v[12:13], v[16:17]
	v_cvt_pk_bf16_f32 v18, v14, v15
	v_mul_f32_e32 v12, 0x3fb8aa3b, v152
	v_mul_f32_e32 v13, 0x3fb8aa3b, v153
	global_store_dword v2, v18, s[16:17]
	s_add_u32 s16, s16, 0x40000
	s_addc_u32 s17, s17, 0
	v_exp_f32_e32 v12, v12
	v_exp_f32_e32 v13, v13
	global_load_dword v36, v2, s[14:15]
	global_load_dwordx2 v[152:153], v4, s[18:19]
	s_add_u32 s14, s14, 0x40000
	s_addc_u32 s15, s15, 0
	s_add_u32 s18, s18, 0x800
	s_addc_u32 s19, s19, 0
	s_waitcnt vmcnt(63)
	v_lshlrev_b32_e32 v16, 16, v37
	v_and_b32_e32 v17, 0xffff0000, v37
	v_pk_mul_f32 v[14:15], v[10:11], v[12:13]
	v_pk_fma_f32 v[10:11], v[10:11], v[12:13], v[16:17]
	v_cvt_pk_bf16_f32 v19, v14, v15
	v_mul_f32_e32 v12, 0x3fb8aa3b, v154
	v_mul_f32_e32 v13, 0x3fb8aa3b, v155
	global_store_dword v2, v19, s[16:17]
	s_add_u32 s16, s16, 0x40000
	s_addc_u32 s17, s17, 0
	v_exp_f32_e32 v12, v12
	v_exp_f32_e32 v13, v13
	global_load_dword v37, v2, s[14:15]
	global_load_dwordx2 v[154:155], v4, s[18:19]
	s_add_u32 s14, s14, 0x40000
	s_addc_u32 s15, s15, 0
	s_add_u32 s18, s18, 0x800
	s_addc_u32 s19, s19, 0
	s_waitcnt vmcnt(63)
	v_lshlrev_b32_e32 v16, 16, v38
	v_and_b32_e32 v17, 0xffff0000, v38
	v_pk_mul_f32 v[14:15], v[10:11], v[12:13]
	v_pk_fma_f32 v[10:11], v[10:11], v[12:13], v[16:17]
	v_cvt_pk_bf16_f32 v22, v14, v15
	v_mul_f32_e32 v12, 0x3fb8aa3b, v170
	v_mul_f32_e32 v13, 0x3fb8aa3b, v171
	global_store_dword v2, v22, s[16:17]
	s_add_u32 s16, s16, 0x40000
	s_addc_u32 s17, s17, 0
	v_exp_f32_e32 v12, v12
	v_exp_f32_e32 v13, v13
	global_load_dword v38, v2, s[14:15]
	global_load_dwordx2 v[170:171], v4, s[18:19]
	s_add_u32 s14, s14, 0x40000
	s_addc_u32 s15, s15, 0
	s_add_u32 s18, s18, 0x800
	s_addc_u32 s19, s19, 0
	s_waitcnt vmcnt(63)
	v_lshlrev_b32_e32 v16, 16, v39
	v_and_b32_e32 v17, 0xffff0000, v39
	v_pk_mul_f32 v[14:15], v[10:11], v[12:13]
	v_pk_fma_f32 v[10:11], v[10:11], v[12:13], v[16:17]
	v_cvt_pk_bf16_f32 v18, v14, v15
	v_mul_f32_e32 v12, 0x3fb8aa3b, v172
	v_mul_f32_e32 v13, 0x3fb8aa3b, v173
	global_store_dword v2, v18, s[16:17]
	s_add_u32 s16, s16, 0x40000
	s_addc_u32 s17, s17, 0
	v_exp_f32_e32 v12, v12
	v_exp_f32_e32 v13, v13
	global_load_dword v39, v2, s[14:15]
	global_load_dwordx2 v[172:173], v4, s[18:19]
	s_add_u32 s14, s14, 0x40000
	s_addc_u32 s15, s15, 0
	s_add_u32 s18, s18, 0x800
	s_addc_u32 s19, s19, 0
	s_waitcnt vmcnt(63)
	v_lshlrev_b32_e32 v16, 16, v40
	v_and_b32_e32 v17, 0xffff0000, v40
	v_pk_mul_f32 v[14:15], v[10:11], v[12:13]
	v_pk_fma_f32 v[10:11], v[10:11], v[12:13], v[16:17]
	v_cvt_pk_bf16_f32 v19, v14, v15
	v_mul_f32_e32 v12, 0x3fb8aa3b, v174
	v_mul_f32_e32 v13, 0x3fb8aa3b, v175
	global_store_dword v2, v19, s[16:17]
	s_add_u32 s16, s16, 0x40000
	s_addc_u32 s17, s17, 0
	v_exp_f32_e32 v12, v12
	v_exp_f32_e32 v13, v13
	global_load_dword v40, v2, s[14:15]
	global_load_dwordx2 v[174:175], v4, s[18:19]
	s_add_u32 s14, s14, 0x40000
	s_addc_u32 s15, s15, 0
	s_add_u32 s18, s18, 0x800
	s_addc_u32 s19, s19, 0
	s_waitcnt vmcnt(63)
	v_lshlrev_b32_e32 v16, 16, v41
	v_and_b32_e32 v17, 0xffff0000, v41
	v_pk_mul_f32 v[14:15], v[10:11], v[12:13]
	v_pk_fma_f32 v[10:11], v[10:11], v[12:13], v[16:17]
	v_cvt_pk_bf16_f32 v22, v14, v15
	v_mul_f32_e32 v12, 0x3fb8aa3b, v176
	v_mul_f32_e32 v13, 0x3fb8aa3b, v177
	global_store_dword v2, v22, s[16:17]
	s_add_u32 s16, s16, 0x40000
	s_addc_u32 s17, s17, 0
	v_exp_f32_e32 v12, v12
	v_exp_f32_e32 v13, v13
	global_load_dword v41, v2, s[14:15]
	global_load_dwordx2 v[176:177], v4, s[18:19]
	s_add_u32 s14, s14, 0x40000
	s_addc_u32 s15, s15, 0
	s_add_u32 s18, s18, 0x800
	s_addc_u32 s19, s19, 0
	s_waitcnt vmcnt(63)
	v_lshlrev_b32_e32 v16, 16, v42
	v_and_b32_e32 v17, 0xffff0000, v42
	v_pk_mul_f32 v[14:15], v[10:11], v[12:13]
	v_pk_fma_f32 v[10:11], v[10:11], v[12:13], v[16:17]
	v_cvt_pk_bf16_f32 v18, v14, v15
	v_mul_f32_e32 v12, 0x3fb8aa3b, v178
	v_mul_f32_e32 v13, 0x3fb8aa3b, v179
	global_store_dword v2, v18, s[16:17]
	s_add_u32 s16, s16, 0x40000
	s_addc_u32 s17, s17, 0
	v_exp_f32_e32 v12, v12
	v_exp_f32_e32 v13, v13
	global_load_dword v42, v2, s[14:15]
	global_load_dwordx2 v[178:179], v4, s[18:19]
	s_add_u32 s14, s14, 0x40000
	s_addc_u32 s15, s15, 0
	s_add_u32 s18, s18, 0x800
	s_addc_u32 s19, s19, 0
	s_waitcnt vmcnt(63)
	v_lshlrev_b32_e32 v16, 16, v43
	v_and_b32_e32 v17, 0xffff0000, v43
	v_pk_mul_f32 v[14:15], v[10:11], v[12:13]
	v_pk_fma_f32 v[10:11], v[10:11], v[12:13], v[16:17]
	v_cvt_pk_bf16_f32 v19, v14, v15
	v_mul_f32_e32 v12, 0x3fb8aa3b, v180
	v_mul_f32_e32 v13, 0x3fb8aa3b, v181
	global_store_dword v2, v19, s[16:17]
	s_add_u32 s16, s16, 0x40000
	s_addc_u32 s17, s17, 0
	v_exp_f32_e32 v12, v12
	v_exp_f32_e32 v13, v13
	global_load_dword v43, v2, s[14:15]
	global_load_dwordx2 v[180:181], v4, s[18:19]
	s_add_u32 s14, s14, 0x40000
	s_addc_u32 s15, s15, 0
	s_add_u32 s18, s18, 0x800
	s_addc_u32 s19, s19, 0
	s_waitcnt vmcnt(63)
	v_lshlrev_b32_e32 v16, 16, v44
	v_and_b32_e32 v17, 0xffff0000, v44
	v_pk_mul_f32 v[14:15], v[10:11], v[12:13]
	v_pk_fma_f32 v[10:11], v[10:11], v[12:13], v[16:17]
	v_cvt_pk_bf16_f32 v22, v14, v15
	v_mul_f32_e32 v12, 0x3fb8aa3b, v182
	v_mul_f32_e32 v13, 0x3fb8aa3b, v183
	global_store_dword v2, v22, s[16:17]
	s_add_u32 s16, s16, 0x40000
	s_addc_u32 s17, s17, 0
	v_exp_f32_e32 v12, v12
	v_exp_f32_e32 v13, v13
	global_load_dword v44, v2, s[14:15]
	global_load_dwordx2 v[182:183], v4, s[18:19]
	s_add_u32 s14, s14, 0x40000
	s_addc_u32 s15, s15, 0
	s_add_u32 s18, s18, 0x800
	s_addc_u32 s19, s19, 0
	s_waitcnt vmcnt(63)
	v_lshlrev_b32_e32 v16, 16, v45
	v_and_b32_e32 v17, 0xffff0000, v45
	v_pk_mul_f32 v[14:15], v[10:11], v[12:13]
	v_pk_fma_f32 v[10:11], v[10:11], v[12:13], v[16:17]
	v_cvt_pk_bf16_f32 v18, v14, v15
	v_mul_f32_e32 v12, 0x3fb8aa3b, v188
	v_mul_f32_e32 v13, 0x3fb8aa3b, v189
	global_store_dword v2, v18, s[16:17]
	s_add_u32 s16, s16, 0x40000
	s_addc_u32 s17, s17, 0
	v_exp_f32_e32 v12, v12
	v_exp_f32_e32 v13, v13
	global_load_dword v45, v2, s[14:15]
	global_load_dwordx2 v[188:189], v4, s[18:19]
	s_add_u32 s14, s14, 0x40000
	s_addc_u32 s15, s15, 0
	s_add_u32 s18, s18, 0x800
	s_addc_u32 s19, s19, 0
	s_waitcnt vmcnt(63)
	v_lshlrev_b32_e32 v16, 16, v46
	v_and_b32_e32 v17, 0xffff0000, v46
	v_pk_mul_f32 v[14:15], v[10:11], v[12:13]
	v_pk_fma_f32 v[10:11], v[10:11], v[12:13], v[16:17]
	v_cvt_pk_bf16_f32 v19, v14, v15
	v_mul_f32_e32 v12, 0x3fb8aa3b, v190
	v_mul_f32_e32 v13, 0x3fb8aa3b, v191
	global_store_dword v2, v19, s[16:17]
	s_add_u32 s16, s16, 0x40000
	s_addc_u32 s17, s17, 0
	v_exp_f32_e32 v12, v12
	v_exp_f32_e32 v13, v13
	global_load_dword v46, v2, s[14:15]
	global_load_dwordx2 v[190:191], v4, s[18:19]
	s_add_u32 s14, s14, 0x40000
	s_addc_u32 s15, s15, 0
	s_add_u32 s18, s18, 0x800
	s_addc_u32 s19, s19, 0
	s_waitcnt vmcnt(63)
	v_lshlrev_b32_e32 v16, 16, v50
	v_and_b32_e32 v17, 0xffff0000, v50
	v_pk_mul_f32 v[14:15], v[10:11], v[12:13]
	v_pk_fma_f32 v[10:11], v[10:11], v[12:13], v[16:17]
	v_cvt_pk_bf16_f32 v22, v14, v15
	v_mul_f32_e32 v12, 0x3fb8aa3b, v192
	v_mul_f32_e32 v13, 0x3fb8aa3b, v193
	global_store_dword v2, v22, s[16:17]
	s_add_u32 s16, s16, 0x40000
	s_addc_u32 s17, s17, 0
	v_exp_f32_e32 v12, v12
	v_exp_f32_e32 v13, v13
	global_load_dword v50, v2, s[14:15]
	global_load_dwordx2 v[192:193], v4, s[18:19]
	s_add_u32 s14, s14, 0x40000
	s_addc_u32 s15, s15, 0
	s_add_u32 s18, s18, 0x800
	s_addc_u32 s19, s19, 0
	s_waitcnt vmcnt(63)
	v_lshlrev_b32_e32 v16, 16, v51
	v_and_b32_e32 v17, 0xffff0000, v51
	v_pk_mul_f32 v[14:15], v[10:11], v[12:13]
	v_pk_fma_f32 v[10:11], v[10:11], v[12:13], v[16:17]
	v_cvt_pk_bf16_f32 v18, v14, v15
	v_mul_f32_e32 v12, 0x3fb8aa3b, v194
	v_mul_f32_e32 v13, 0x3fb8aa3b, v195
	global_store_dword v2, v18, s[16:17]
	s_add_u32 s16, s16, 0x40000
	s_addc_u32 s17, s17, 0
	v_exp_f32_e32 v12, v12
	v_exp_f32_e32 v13, v13
	global_load_dword v51, v2, s[14:15]
	global_load_dwordx2 v[194:195], v4, s[18:19]
	s_add_u32 s14, s14, 0x40000
	s_addc_u32 s15, s15, 0
	s_add_u32 s18, s18, 0x800
	s_addc_u32 s19, s19, 0
	s_waitcnt vmcnt(63)
	v_lshlrev_b32_e32 v16, 16, v52
	v_and_b32_e32 v17, 0xffff0000, v52
	v_pk_mul_f32 v[14:15], v[10:11], v[12:13]
	v_pk_fma_f32 v[10:11], v[10:11], v[12:13], v[16:17]
	v_cvt_pk_bf16_f32 v19, v14, v15
	v_mul_f32_e32 v12, 0x3fb8aa3b, v196
	v_mul_f32_e32 v13, 0x3fb8aa3b, v197
	global_store_dword v2, v19, s[16:17]
	s_add_u32 s16, s16, 0x40000
	s_addc_u32 s17, s17, 0
	v_exp_f32_e32 v12, v12
	v_exp_f32_e32 v13, v13
	global_load_dword v52, v2, s[14:15]
	global_load_dwordx2 v[196:197], v4, s[18:19]
	s_add_u32 s14, s14, 0x40000
	s_addc_u32 s15, s15, 0
	s_add_u32 s18, s18, 0x800
	s_addc_u32 s19, s19, 0
	s_waitcnt vmcnt(63)
	v_lshlrev_b32_e32 v16, 16, v53
	v_and_b32_e32 v17, 0xffff0000, v53
	v_pk_mul_f32 v[14:15], v[10:11], v[12:13]
	v_pk_fma_f32 v[10:11], v[10:11], v[12:13], v[16:17]
	v_cvt_pk_bf16_f32 v22, v14, v15
	v_mul_f32_e32 v12, 0x3fb8aa3b, v198
	v_mul_f32_e32 v13, 0x3fb8aa3b, v199
	global_store_dword v2, v22, s[16:17]
	s_add_u32 s16, s16, 0x40000
	s_addc_u32 s17, s17, 0
	v_exp_f32_e32 v12, v12
	v_exp_f32_e32 v13, v13
	global_load_dword v53, v2, s[14:15]
	global_load_dwordx2 v[198:199], v4, s[18:19]
	s_add_u32 s14, s14, 0x40000
	s_addc_u32 s15, s15, 0
	s_add_u32 s18, s18, 0x800
	s_addc_u32 s19, s19, 0
	s_waitcnt vmcnt(63)
	v_lshlrev_b32_e32 v16, 16, v54
	v_and_b32_e32 v17, 0xffff0000, v54
	v_pk_mul_f32 v[14:15], v[10:11], v[12:13]
	v_pk_fma_f32 v[10:11], v[10:11], v[12:13], v[16:17]
	v_cvt_pk_bf16_f32 v18, v14, v15
	v_mul_f32_e32 v12, 0x3fb8aa3b, v202
	v_mul_f32_e32 v13, 0x3fb8aa3b, v203
	global_store_dword v2, v18, s[16:17]
	s_add_u32 s16, s16, 0x40000
	s_addc_u32 s17, s17, 0
	v_exp_f32_e32 v12, v12
	v_exp_f32_e32 v13, v13
	global_load_dword v54, v2, s[14:15]
	global_load_dwordx2 v[202:203], v4, s[18:19]
	s_add_u32 s14, s14, 0x40000
	s_addc_u32 s15, s15, 0
	s_add_u32 s18, s18, 0x800
	s_addc_u32 s19, s19, 0
	s_waitcnt vmcnt(63)
	v_lshlrev_b32_e32 v16, 16, v55
	v_and_b32_e32 v17, 0xffff0000, v55
	v_pk_mul_f32 v[14:15], v[10:11], v[12:13]
	v_pk_fma_f32 v[10:11], v[10:11], v[12:13], v[16:17]
	v_cvt_pk_bf16_f32 v19, v14, v15
	v_mul_f32_e32 v12, 0x3fb8aa3b, v204
	v_mul_f32_e32 v13, 0x3fb8aa3b, v205
	global_store_dword v2, v19, s[16:17]
	s_add_u32 s16, s16, 0x40000
	s_addc_u32 s17, s17, 0
	v_exp_f32_e32 v12, v12
	v_exp_f32_e32 v13, v13
	global_load_dword v55, v2, s[14:15]
	global_load_dwordx2 v[204:205], v4, s[18:19]
	s_add_u32 s14, s14, 0x40000
	s_addc_u32 s15, s15, 0
	s_add_u32 s18, s18, 0x800
	s_addc_u32 s19, s19, 0
	s_waitcnt vmcnt(63)
	v_lshlrev_b32_e32 v16, 16, v56
	v_and_b32_e32 v17, 0xffff0000, v56
	v_pk_mul_f32 v[14:15], v[10:11], v[12:13]
	v_pk_fma_f32 v[10:11], v[10:11], v[12:13], v[16:17]
	v_cvt_pk_bf16_f32 v22, v14, v15
	v_mul_f32_e32 v12, 0x3fb8aa3b, v206
	v_mul_f32_e32 v13, 0x3fb8aa3b, v207
	global_store_dword v2, v22, s[16:17]
	s_add_u32 s16, s16, 0x40000
	s_addc_u32 s17, s17, 0
	v_exp_f32_e32 v12, v12
	v_exp_f32_e32 v13, v13
	global_load_dword v56, v2, s[14:15]
	global_load_dwordx2 v[206:207], v4, s[18:19]
	s_add_u32 s14, s14, 0x40000
	s_addc_u32 s15, s15, 0
	s_add_u32 s18, s18, 0x800
	s_addc_u32 s19, s19, 0
	s_waitcnt vmcnt(63)
	v_lshlrev_b32_e32 v16, 16, v57
	v_and_b32_e32 v17, 0xffff0000, v57
	v_pk_mul_f32 v[14:15], v[10:11], v[12:13]
	v_pk_fma_f32 v[10:11], v[10:11], v[12:13], v[16:17]
	v_cvt_pk_bf16_f32 v18, v14, v15
	v_mul_f32_e32 v12, 0x3fb8aa3b, v208
	v_mul_f32_e32 v13, 0x3fb8aa3b, v209
	global_store_dword v2, v18, s[16:17]
	s_add_u32 s16, s16, 0x40000
	s_addc_u32 s17, s17, 0
	v_exp_f32_e32 v12, v12
	v_exp_f32_e32 v13, v13
	global_load_dword v57, v2, s[14:15]
	global_load_dwordx2 v[208:209], v4, s[18:19]
	s_add_u32 s14, s14, 0x40000
	s_addc_u32 s15, s15, 0
	s_add_u32 s18, s18, 0x800
	s_addc_u32 s19, s19, 0
	s_waitcnt vmcnt(63)
	v_lshlrev_b32_e32 v16, 16, v58
	v_and_b32_e32 v17, 0xffff0000, v58
	v_pk_mul_f32 v[14:15], v[10:11], v[12:13]
	v_pk_fma_f32 v[10:11], v[10:11], v[12:13], v[16:17]
	v_cvt_pk_bf16_f32 v19, v14, v15
	v_mul_f32_e32 v12, 0x3fb8aa3b, v210
	v_mul_f32_e32 v13, 0x3fb8aa3b, v211
	global_store_dword v2, v19, s[16:17]
	s_add_u32 s16, s16, 0x40000
	s_addc_u32 s17, s17, 0
	v_exp_f32_e32 v12, v12
	v_exp_f32_e32 v13, v13
	global_load_dword v58, v2, s[14:15]
	global_load_dwordx2 v[210:211], v4, s[18:19]
	s_add_u32 s14, s14, 0x40000
	s_addc_u32 s15, s15, 0
	s_add_u32 s18, s18, 0x800
	s_addc_u32 s19, s19, 0
	s_waitcnt vmcnt(63)
	v_lshlrev_b32_e32 v16, 16, v59
	v_and_b32_e32 v17, 0xffff0000, v59
	v_pk_mul_f32 v[14:15], v[10:11], v[12:13]
	v_pk_fma_f32 v[10:11], v[10:11], v[12:13], v[16:17]
	v_cvt_pk_bf16_f32 v22, v14, v15
	v_mul_f32_e32 v12, 0x3fb8aa3b, v212
	v_mul_f32_e32 v13, 0x3fb8aa3b, v213
	global_store_dword v2, v22, s[16:17]
	s_add_u32 s16, s16, 0x40000
	s_addc_u32 s17, s17, 0
	v_exp_f32_e32 v12, v12
	v_exp_f32_e32 v13, v13
	global_load_dword v59, v2, s[14:15]
	global_load_dwordx2 v[212:213], v4, s[18:19]
	s_add_u32 s14, s14, 0x40000
	s_addc_u32 s15, s15, 0
	s_add_u32 s18, s18, 0x800
	s_addc_u32 s19, s19, 0
	s_waitcnt vmcnt(63)
	v_lshlrev_b32_e32 v16, 16, v60
	v_and_b32_e32 v17, 0xffff0000, v60
	v_pk_mul_f32 v[14:15], v[10:11], v[12:13]
	v_pk_fma_f32 v[10:11], v[10:11], v[12:13], v[16:17]
	v_cvt_pk_bf16_f32 v18, v14, v15
	v_mul_f32_e32 v12, 0x3fb8aa3b, v214
	v_mul_f32_e32 v13, 0x3fb8aa3b, v215
	global_store_dword v2, v18, s[16:17]
	s_add_u32 s16, s16, 0x40000
	s_addc_u32 s17, s17, 0
	v_exp_f32_e32 v12, v12
	v_exp_f32_e32 v13, v13
	global_load_dword v60, v2, s[14:15]
	global_load_dwordx2 v[214:215], v4, s[18:19]
	s_add_u32 s14, s14, 0x40000
	s_addc_u32 s15, s15, 0
	s_add_u32 s18, s18, 0x800
	s_addc_u32 s19, s19, 0
	s_waitcnt vmcnt(63)
	v_lshlrev_b32_e32 v16, 16, v61
	v_and_b32_e32 v17, 0xffff0000, v61
	v_pk_mul_f32 v[14:15], v[10:11], v[12:13]
	v_pk_fma_f32 v[10:11], v[10:11], v[12:13], v[16:17]
	v_cvt_pk_bf16_f32 v19, v14, v15
	v_mul_f32_e32 v12, 0x3fb8aa3b, v216
	v_mul_f32_e32 v13, 0x3fb8aa3b, v217
	global_store_dword v2, v19, s[16:17]
	s_add_u32 s16, s16, 0x40000
	s_addc_u32 s17, s17, 0
	v_exp_f32_e32 v12, v12
	v_exp_f32_e32 v13, v13
	global_load_dword v61, v2, s[14:15]
	global_load_dwordx2 v[216:217], v4, s[18:19]
	s_add_u32 s14, s14, 0x40000
	s_addc_u32 s15, s15, 0
	s_add_u32 s18, s18, 0x800
	s_addc_u32 s19, s19, 0
	s_waitcnt vmcnt(63)
	v_lshlrev_b32_e32 v16, 16, v27
	v_and_b32_e32 v17, 0xffff0000, v27
	v_pk_mul_f32 v[14:15], v[10:11], v[12:13]
	s_nop 0
	v_pk_add_f32 v[10:11], v[14:15], v[16:17]
	v_cvt_pk_bf16_f32 v22, v14, v15
	v_mul_f32_e32 v12, 0x3fb8aa3b, v134
	v_mul_f32_e32 v13, 0x3fb8aa3b, v135
	global_store_dword v2, v22, s[16:17]
	s_add_u32 s16, s16, 0x40000
	s_addc_u32 s17, s17, 0
	v_exp_f32_e32 v12, v12
	v_exp_f32_e32 v13, v13
	global_load_dword v27, v2, s[14:15]
	global_load_dwordx2 v[134:135], v4, s[18:19]
	s_add_u32 s14, s14, 0x40000
	s_addc_u32 s15, s15, 0
	s_add_u32 s18, s18, 0x800
	s_addc_u32 s19, s19, 0
	s_waitcnt vmcnt(63)
	v_lshlrev_b32_e32 v16, 16, v28
	v_and_b32_e32 v17, 0xffff0000, v28
	v_pk_mul_f32 v[14:15], v[10:11], v[12:13]
	v_pk_fma_f32 v[10:11], v[10:11], v[12:13], v[16:17]
	v_cvt_pk_bf16_f32 v18, v14, v15
	v_mul_f32_e32 v12, 0x3fb8aa3b, v136
	v_mul_f32_e32 v13, 0x3fb8aa3b, v137
	global_store_dword v2, v18, s[16:17]
	s_add_u32 s16, s16, 0x40000
	s_addc_u32 s17, s17, 0
	v_exp_f32_e32 v12, v12
	v_exp_f32_e32 v13, v13
	global_load_dword v28, v2, s[14:15]
	global_load_dwordx2 v[136:137], v4, s[18:19]
	s_add_u32 s14, s14, 0x40000
	s_addc_u32 s15, s15, 0
	s_add_u32 s18, s18, 0x800
	s_addc_u32 s19, s19, 0
	s_waitcnt vmcnt(63)
	v_lshlrev_b32_e32 v16, 16, v29
	v_and_b32_e32 v17, 0xffff0000, v29
	v_pk_mul_f32 v[14:15], v[10:11], v[12:13]
	v_pk_fma_f32 v[10:11], v[10:11], v[12:13], v[16:17]
	v_cvt_pk_bf16_f32 v19, v14, v15
	v_mul_f32_e32 v12, 0x3fb8aa3b, v138
	v_mul_f32_e32 v13, 0x3fb8aa3b, v139
	global_store_dword v2, v19, s[16:17]
	s_add_u32 s16, s16, 0x40000
	s_addc_u32 s17, s17, 0
	v_exp_f32_e32 v12, v12
	v_exp_f32_e32 v13, v13
	global_load_dword v29, v2, s[14:15]
	global_load_dwordx2 v[138:139], v4, s[18:19]
	s_add_u32 s14, s14, 0x40000
	s_addc_u32 s15, s15, 0
	s_add_u32 s18, s18, 0x800
	s_addc_u32 s19, s19, 0
	s_waitcnt vmcnt(63)
	v_lshlrev_b32_e32 v16, 16, v30
	v_and_b32_e32 v17, 0xffff0000, v30
	v_pk_mul_f32 v[14:15], v[10:11], v[12:13]
	v_pk_fma_f32 v[10:11], v[10:11], v[12:13], v[16:17]
	v_cvt_pk_bf16_f32 v22, v14, v15
	v_mul_f32_e32 v12, 0x3fb8aa3b, v140
	v_mul_f32_e32 v13, 0x3fb8aa3b, v141
	global_store_dword v2, v22, s[16:17]
	s_add_u32 s16, s16, 0x40000
	s_addc_u32 s17, s17, 0
	v_exp_f32_e32 v12, v12
	v_exp_f32_e32 v13, v13
	global_load_dword v30, v2, s[14:15]
	global_load_dwordx2 v[140:141], v4, s[18:19]
	s_add_u32 s14, s14, 0x40000
	s_addc_u32 s15, s15, 0
	s_add_u32 s18, s18, 0x800
	s_addc_u32 s19, s19, 0
	s_waitcnt vmcnt(63)
	v_lshlrev_b32_e32 v16, 16, v31
	v_and_b32_e32 v17, 0xffff0000, v31
	v_pk_mul_f32 v[14:15], v[10:11], v[12:13]
	v_pk_fma_f32 v[10:11], v[10:11], v[12:13], v[16:17]
	v_cvt_pk_bf16_f32 v18, v14, v15
	v_mul_f32_e32 v12, 0x3fb8aa3b, v142
	v_mul_f32_e32 v13, 0x3fb8aa3b, v143
	global_store_dword v2, v18, s[16:17]
	s_add_u32 s16, s16, 0x40000
	s_addc_u32 s17, s17, 0
	v_exp_f32_e32 v12, v12
	v_exp_f32_e32 v13, v13
	global_load_dword v31, v2, s[14:15]
	global_load_dwordx2 v[142:143], v4, s[18:19]
	s_add_u32 s14, s14, 0x40000
	s_addc_u32 s15, s15, 0
	s_add_u32 s18, s18, 0x800
	s_addc_u32 s19, s19, 0
	s_waitcnt vmcnt(63)
	v_lshlrev_b32_e32 v16, 16, v32
	v_and_b32_e32 v17, 0xffff0000, v32
	v_pk_mul_f32 v[14:15], v[10:11], v[12:13]
	v_pk_fma_f32 v[10:11], v[10:11], v[12:13], v[16:17]
	v_cvt_pk_bf16_f32 v19, v14, v15
	v_mul_f32_e32 v12, 0x3fb8aa3b, v144
	v_mul_f32_e32 v13, 0x3fb8aa3b, v145
	global_store_dword v2, v19, s[16:17]
	s_add_u32 s16, s16, 0x40000
	s_addc_u32 s17, s17, 0
	v_exp_f32_e32 v12, v12
	v_exp_f32_e32 v13, v13
	global_load_dword v32, v2, s[14:15]
	global_load_dwordx2 v[144:145], v4, s[18:19]
	s_add_u32 s14, s14, 0x40000
	s_addc_u32 s15, s15, 0
	s_add_u32 s18, s18, 0x800
	s_addc_u32 s19, s19, 0
	s_waitcnt vmcnt(63)
	v_lshlrev_b32_e32 v16, 16, v33
	v_and_b32_e32 v17, 0xffff0000, v33
	v_pk_mul_f32 v[14:15], v[10:11], v[12:13]
	v_pk_fma_f32 v[10:11], v[10:11], v[12:13], v[16:17]
	v_cvt_pk_bf16_f32 v22, v14, v15
	v_mul_f32_e32 v12, 0x3fb8aa3b, v146
	v_mul_f32_e32 v13, 0x3fb8aa3b, v147
	global_store_dword v2, v22, s[16:17]
	s_add_u32 s16, s16, 0x40000
	s_addc_u32 s17, s17, 0
	v_exp_f32_e32 v12, v12
	v_exp_f32_e32 v13, v13
	global_load_dword v33, v2, s[14:15]
	global_load_dwordx2 v[146:147], v4, s[18:19]
	s_add_u32 s14, s14, 0x40000
	s_addc_u32 s15, s15, 0
	s_add_u32 s18, s18, 0x800
	s_addc_u32 s19, s19, 0
	s_waitcnt vmcnt(63)
	v_lshlrev_b32_e32 v16, 16, v34
	v_and_b32_e32 v17, 0xffff0000, v34
	v_pk_mul_f32 v[14:15], v[10:11], v[12:13]
	v_pk_fma_f32 v[10:11], v[10:11], v[12:13], v[16:17]
	v_cvt_pk_bf16_f32 v18, v14, v15
	v_mul_f32_e32 v12, 0x3fb8aa3b, v148
	v_mul_f32_e32 v13, 0x3fb8aa3b, v149
	global_store_dword v2, v18, s[16:17]
	s_add_u32 s16, s16, 0x40000
	s_addc_u32 s17, s17, 0
	v_exp_f32_e32 v12, v12
	v_exp_f32_e32 v13, v13
	global_load_dword v34, v2, s[14:15]
	global_load_dwordx2 v[148:149], v4, s[18:19]
	s_add_u32 s14, s14, 0x40000
	s_addc_u32 s15, s15, 0
	s_add_u32 s18, s18, 0x800
	s_addc_u32 s19, s19, 0
	s_waitcnt vmcnt(63)
	v_lshlrev_b32_e32 v16, 16, v35
	v_and_b32_e32 v17, 0xffff0000, v35
	v_pk_mul_f32 v[14:15], v[10:11], v[12:13]
	v_pk_fma_f32 v[10:11], v[10:11], v[12:13], v[16:17]
	v_cvt_pk_bf16_f32 v19, v14, v15
	v_mul_f32_e32 v12, 0x3fb8aa3b, v150
	v_mul_f32_e32 v13, 0x3fb8aa3b, v151
	global_store_dword v2, v19, s[16:17]
	s_add_u32 s16, s16, 0x40000
	s_addc_u32 s17, s17, 0
	v_exp_f32_e32 v12, v12
	v_exp_f32_e32 v13, v13
	global_load_dword v35, v2, s[14:15]
	global_load_dwordx2 v[150:151], v4, s[18:19]
	s_add_u32 s14, s14, 0x40000
	s_addc_u32 s15, s15, 0
	s_add_u32 s18, s18, 0x800
	s_addc_u32 s19, s19, 0
	s_waitcnt vmcnt(63)
	v_lshlrev_b32_e32 v16, 16, v36
	v_and_b32_e32 v17, 0xffff0000, v36
	v_pk_mul_f32 v[14:15], v[10:11], v[12:13]
	v_pk_fma_f32 v[10:11], v[10:11], v[12:13], v[16:17]
	v_cvt_pk_bf16_f32 v22, v14, v15
	v_mul_f32_e32 v12, 0x3fb8aa3b, v152
	v_mul_f32_e32 v13, 0x3fb8aa3b, v153
	global_store_dword v2, v22, s[16:17]
	s_add_u32 s16, s16, 0x40000
	s_addc_u32 s17, s17, 0
	v_exp_f32_e32 v12, v12
	v_exp_f32_e32 v13, v13
	global_load_dword v36, v2, s[14:15]
	global_load_dwordx2 v[152:153], v4, s[18:19]
	s_add_u32 s14, s14, 0x40000
	s_addc_u32 s15, s15, 0
	s_add_u32 s18, s18, 0x800
	s_addc_u32 s19, s19, 0
	s_waitcnt vmcnt(63)
	v_lshlrev_b32_e32 v16, 16, v37
	v_and_b32_e32 v17, 0xffff0000, v37
	v_pk_mul_f32 v[14:15], v[10:11], v[12:13]
	v_pk_fma_f32 v[10:11], v[10:11], v[12:13], v[16:17]
	v_cvt_pk_bf16_f32 v18, v14, v15
	v_mul_f32_e32 v12, 0x3fb8aa3b, v154
	v_mul_f32_e32 v13, 0x3fb8aa3b, v155
	global_store_dword v2, v18, s[16:17]
	s_add_u32 s16, s16, 0x40000
	s_addc_u32 s17, s17, 0
	v_exp_f32_e32 v12, v12
	v_exp_f32_e32 v13, v13
	global_load_dword v37, v2, s[14:15]
	global_load_dwordx2 v[154:155], v4, s[18:19]
	s_add_u32 s14, s14, 0x40000
	s_addc_u32 s15, s15, 0
	s_add_u32 s18, s18, 0x800
	s_addc_u32 s19, s19, 0
	s_waitcnt vmcnt(63)
	v_lshlrev_b32_e32 v16, 16, v38
	v_and_b32_e32 v17, 0xffff0000, v38
	v_pk_mul_f32 v[14:15], v[10:11], v[12:13]
	v_pk_fma_f32 v[10:11], v[10:11], v[12:13], v[16:17]
	v_cvt_pk_bf16_f32 v19, v14, v15
	v_mul_f32_e32 v12, 0x3fb8aa3b, v170
	v_mul_f32_e32 v13, 0x3fb8aa3b, v171
	global_store_dword v2, v19, s[16:17]
	s_add_u32 s16, s16, 0x40000
	s_addc_u32 s17, s17, 0
	v_exp_f32_e32 v12, v12
	v_exp_f32_e32 v13, v13
	global_load_dword v38, v2, s[14:15]
	global_load_dwordx2 v[170:171], v4, s[18:19]
	s_add_u32 s14, s14, 0x40000
	s_addc_u32 s15, s15, 0
	s_add_u32 s18, s18, 0x800
	s_addc_u32 s19, s19, 0
	s_waitcnt vmcnt(63)
	v_lshlrev_b32_e32 v16, 16, v39
	v_and_b32_e32 v17, 0xffff0000, v39
	v_pk_mul_f32 v[14:15], v[10:11], v[12:13]
	v_pk_fma_f32 v[10:11], v[10:11], v[12:13], v[16:17]
	v_cvt_pk_bf16_f32 v22, v14, v15
	v_mul_f32_e32 v12, 0x3fb8aa3b, v172
	v_mul_f32_e32 v13, 0x3fb8aa3b, v173
	global_store_dword v2, v22, s[16:17]
	s_add_u32 s16, s16, 0x40000
	s_addc_u32 s17, s17, 0
	v_exp_f32_e32 v12, v12
	v_exp_f32_e32 v13, v13
	global_load_dword v39, v2, s[14:15]
	global_load_dwordx2 v[172:173], v4, s[18:19]
	s_add_u32 s14, s14, 0x40000
	s_addc_u32 s15, s15, 0
	s_add_u32 s18, s18, 0x800
	s_addc_u32 s19, s19, 0
	s_waitcnt vmcnt(63)
	v_lshlrev_b32_e32 v16, 16, v40
	v_and_b32_e32 v17, 0xffff0000, v40
	v_pk_mul_f32 v[14:15], v[10:11], v[12:13]
	v_pk_fma_f32 v[10:11], v[10:11], v[12:13], v[16:17]
	v_cvt_pk_bf16_f32 v18, v14, v15
	v_mul_f32_e32 v12, 0x3fb8aa3b, v174
	v_mul_f32_e32 v13, 0x3fb8aa3b, v175
	global_store_dword v2, v18, s[16:17]
	s_add_u32 s16, s16, 0x40000
	s_addc_u32 s17, s17, 0
	v_exp_f32_e32 v12, v12
	v_exp_f32_e32 v13, v13
	global_load_dword v40, v2, s[14:15]
	global_load_dwordx2 v[174:175], v4, s[18:19]
	s_add_u32 s14, s14, 0x40000
	s_addc_u32 s15, s15, 0
	s_add_u32 s18, s18, 0x800
	s_addc_u32 s19, s19, 0
	s_waitcnt vmcnt(63)
	v_lshlrev_b32_e32 v16, 16, v41
	v_and_b32_e32 v17, 0xffff0000, v41
	v_pk_mul_f32 v[14:15], v[10:11], v[12:13]
	v_pk_fma_f32 v[10:11], v[10:11], v[12:13], v[16:17]
	v_cvt_pk_bf16_f32 v19, v14, v15
	v_mul_f32_e32 v12, 0x3fb8aa3b, v176
	v_mul_f32_e32 v13, 0x3fb8aa3b, v177
	global_store_dword v2, v19, s[16:17]
	s_add_u32 s16, s16, 0x40000
	s_addc_u32 s17, s17, 0
	v_exp_f32_e32 v12, v12
	v_exp_f32_e32 v13, v13
	global_load_dword v41, v2, s[14:15]
	global_load_dwordx2 v[176:177], v4, s[18:19]
	s_add_u32 s14, s14, 0x40000
	s_addc_u32 s15, s15, 0
	s_add_u32 s18, s18, 0x800
	s_addc_u32 s19, s19, 0
	s_waitcnt vmcnt(63)
	v_lshlrev_b32_e32 v16, 16, v42
	v_and_b32_e32 v17, 0xffff0000, v42
	v_pk_mul_f32 v[14:15], v[10:11], v[12:13]
	v_pk_fma_f32 v[10:11], v[10:11], v[12:13], v[16:17]
	v_cvt_pk_bf16_f32 v22, v14, v15
	v_mul_f32_e32 v12, 0x3fb8aa3b, v178
	v_mul_f32_e32 v13, 0x3fb8aa3b, v179
	global_store_dword v2, v22, s[16:17]
	s_add_u32 s16, s16, 0x40000
	s_addc_u32 s17, s17, 0
	v_exp_f32_e32 v12, v12
	v_exp_f32_e32 v13, v13
	global_load_dword v42, v2, s[14:15]
	global_load_dwordx2 v[178:179], v4, s[18:19]
	s_add_u32 s14, s14, 0x40000
	s_addc_u32 s15, s15, 0
	s_add_u32 s18, s18, 0x800
	s_addc_u32 s19, s19, 0
	s_waitcnt vmcnt(63)
	v_lshlrev_b32_e32 v16, 16, v43
	v_and_b32_e32 v17, 0xffff0000, v43
	v_pk_mul_f32 v[14:15], v[10:11], v[12:13]
	v_pk_fma_f32 v[10:11], v[10:11], v[12:13], v[16:17]
	v_cvt_pk_bf16_f32 v18, v14, v15
	v_mul_f32_e32 v12, 0x3fb8aa3b, v180
	v_mul_f32_e32 v13, 0x3fb8aa3b, v181
	global_store_dword v2, v18, s[16:17]
	s_add_u32 s16, s16, 0x40000
	s_addc_u32 s17, s17, 0
	v_exp_f32_e32 v12, v12
	v_exp_f32_e32 v13, v13
	global_load_dword v43, v2, s[14:15]
	global_load_dwordx2 v[180:181], v4, s[18:19]
	s_add_u32 s14, s14, 0x40000
	s_addc_u32 s15, s15, 0
	s_add_u32 s18, s18, 0x800
	s_addc_u32 s19, s19, 0
	s_waitcnt vmcnt(63)
	v_lshlrev_b32_e32 v16, 16, v44
	v_and_b32_e32 v17, 0xffff0000, v44
	v_pk_mul_f32 v[14:15], v[10:11], v[12:13]
	v_pk_fma_f32 v[10:11], v[10:11], v[12:13], v[16:17]
	v_cvt_pk_bf16_f32 v19, v14, v15
	v_mul_f32_e32 v12, 0x3fb8aa3b, v182
	v_mul_f32_e32 v13, 0x3fb8aa3b, v183
	global_store_dword v2, v19, s[16:17]
	s_add_u32 s16, s16, 0x40000
	s_addc_u32 s17, s17, 0
	v_exp_f32_e32 v12, v12
	v_exp_f32_e32 v13, v13
	global_load_dword v44, v2, s[14:15]
	global_load_dwordx2 v[182:183], v4, s[18:19]
	s_add_u32 s14, s14, 0x40000
	s_addc_u32 s15, s15, 0
	s_add_u32 s18, s18, 0x800
	s_addc_u32 s19, s19, 0
	s_waitcnt vmcnt(63)
	v_lshlrev_b32_e32 v16, 16, v45
	v_and_b32_e32 v17, 0xffff0000, v45
	v_pk_mul_f32 v[14:15], v[10:11], v[12:13]
	v_pk_fma_f32 v[10:11], v[10:11], v[12:13], v[16:17]
	v_cvt_pk_bf16_f32 v22, v14, v15
	v_mul_f32_e32 v12, 0x3fb8aa3b, v188
	v_mul_f32_e32 v13, 0x3fb8aa3b, v189
	global_store_dword v2, v22, s[16:17]
	s_add_u32 s16, s16, 0x40000
	s_addc_u32 s17, s17, 0
	v_exp_f32_e32 v12, v12
	v_exp_f32_e32 v13, v13
	global_load_dword v45, v2, s[14:15]
	global_load_dwordx2 v[188:189], v4, s[18:19]
	s_add_u32 s14, s14, 0x40000
	s_addc_u32 s15, s15, 0
	s_add_u32 s18, s18, 0x800
	s_addc_u32 s19, s19, 0
	s_waitcnt vmcnt(63)
	v_lshlrev_b32_e32 v16, 16, v46
	v_and_b32_e32 v17, 0xffff0000, v46
	v_pk_mul_f32 v[14:15], v[10:11], v[12:13]
	v_pk_fma_f32 v[10:11], v[10:11], v[12:13], v[16:17]
	v_cvt_pk_bf16_f32 v18, v14, v15
	v_mul_f32_e32 v12, 0x3fb8aa3b, v190
	v_mul_f32_e32 v13, 0x3fb8aa3b, v191
	global_store_dword v2, v18, s[16:17]
	s_add_u32 s16, s16, 0x40000
	s_addc_u32 s17, s17, 0
	v_exp_f32_e32 v12, v12
	v_exp_f32_e32 v13, v13
	global_load_dword v46, v2, s[14:15]
	global_load_dwordx2 v[190:191], v4, s[18:19]
	s_add_u32 s14, s14, 0x40000
	s_addc_u32 s15, s15, 0
	s_add_u32 s18, s18, 0x800
	s_addc_u32 s19, s19, 0
	s_waitcnt vmcnt(63)
	v_lshlrev_b32_e32 v16, 16, v50
	v_and_b32_e32 v17, 0xffff0000, v50
	v_pk_mul_f32 v[14:15], v[10:11], v[12:13]
	v_pk_fma_f32 v[10:11], v[10:11], v[12:13], v[16:17]
	v_cvt_pk_bf16_f32 v19, v14, v15
	v_mul_f32_e32 v12, 0x3fb8aa3b, v192
	v_mul_f32_e32 v13, 0x3fb8aa3b, v193
	global_store_dword v2, v19, s[16:17]
	s_add_u32 s16, s16, 0x40000
	s_addc_u32 s17, s17, 0
	v_exp_f32_e32 v12, v12
	v_exp_f32_e32 v13, v13
	global_load_dword v50, v2, s[14:15]
	global_load_dwordx2 v[192:193], v4, s[18:19]
	s_add_u32 s14, s14, 0x40000
	s_addc_u32 s15, s15, 0
	s_add_u32 s18, s18, 0x800
	s_addc_u32 s19, s19, 0
	s_waitcnt vmcnt(63)
	v_lshlrev_b32_e32 v16, 16, v51
	v_and_b32_e32 v17, 0xffff0000, v51
	v_pk_mul_f32 v[14:15], v[10:11], v[12:13]
	v_pk_fma_f32 v[10:11], v[10:11], v[12:13], v[16:17]
	v_cvt_pk_bf16_f32 v22, v14, v15
	v_mul_f32_e32 v12, 0x3fb8aa3b, v194
	v_mul_f32_e32 v13, 0x3fb8aa3b, v195
	global_store_dword v2, v22, s[16:17]
	s_add_u32 s16, s16, 0x40000
	s_addc_u32 s17, s17, 0
	v_exp_f32_e32 v12, v12
	v_exp_f32_e32 v13, v13
	global_load_dword v51, v2, s[14:15]
	global_load_dwordx2 v[194:195], v4, s[18:19]
	s_add_u32 s14, s14, 0x40000
	s_addc_u32 s15, s15, 0
	s_add_u32 s18, s18, 0x800
	s_addc_u32 s19, s19, 0
	s_waitcnt vmcnt(63)
	v_lshlrev_b32_e32 v16, 16, v52
	v_and_b32_e32 v17, 0xffff0000, v52
	v_pk_mul_f32 v[14:15], v[10:11], v[12:13]
	v_pk_fma_f32 v[10:11], v[10:11], v[12:13], v[16:17]
	v_cvt_pk_bf16_f32 v18, v14, v15
	v_mul_f32_e32 v12, 0x3fb8aa3b, v196
	v_mul_f32_e32 v13, 0x3fb8aa3b, v197
	global_store_dword v2, v18, s[16:17]
	s_add_u32 s16, s16, 0x40000
	s_addc_u32 s17, s17, 0
	v_exp_f32_e32 v12, v12
	v_exp_f32_e32 v13, v13
	global_load_dword v52, v2, s[14:15]
	global_load_dwordx2 v[196:197], v4, s[18:19]
	s_add_u32 s14, s14, 0x40000
	s_addc_u32 s15, s15, 0
	s_add_u32 s18, s18, 0x800
	s_addc_u32 s19, s19, 0
	s_waitcnt vmcnt(63)
	v_lshlrev_b32_e32 v16, 16, v53
	v_and_b32_e32 v17, 0xffff0000, v53
	v_pk_mul_f32 v[14:15], v[10:11], v[12:13]
	v_pk_fma_f32 v[10:11], v[10:11], v[12:13], v[16:17]
	v_cvt_pk_bf16_f32 v19, v14, v15
	v_mul_f32_e32 v12, 0x3fb8aa3b, v198
	v_mul_f32_e32 v13, 0x3fb8aa3b, v199
	global_store_dword v2, v19, s[16:17]
	s_add_u32 s16, s16, 0x40000
	s_addc_u32 s17, s17, 0
	v_exp_f32_e32 v12, v12
	v_exp_f32_e32 v13, v13
	global_load_dword v53, v2, s[14:15]
	global_load_dwordx2 v[198:199], v4, s[18:19]
	s_add_u32 s14, s14, 0x40000
	s_addc_u32 s15, s15, 0
	s_add_u32 s18, s18, 0x800
	s_addc_u32 s19, s19, 0
	s_waitcnt vmcnt(63)
	v_lshlrev_b32_e32 v16, 16, v54
	v_and_b32_e32 v17, 0xffff0000, v54
	v_pk_mul_f32 v[14:15], v[10:11], v[12:13]
	v_pk_fma_f32 v[10:11], v[10:11], v[12:13], v[16:17]
	v_cvt_pk_bf16_f32 v22, v14, v15
	v_mul_f32_e32 v12, 0x3fb8aa3b, v202
	v_mul_f32_e32 v13, 0x3fb8aa3b, v203
	global_store_dword v2, v22, s[16:17]
	s_add_u32 s16, s16, 0x40000
	s_addc_u32 s17, s17, 0
	v_exp_f32_e32 v12, v12
	v_exp_f32_e32 v13, v13
	global_load_dword v54, v2, s[14:15]
	global_load_dwordx2 v[202:203], v4, s[18:19]
	s_add_u32 s14, s14, 0x40000
	s_addc_u32 s15, s15, 0
	s_add_u32 s18, s18, 0x800
	s_addc_u32 s19, s19, 0
	s_waitcnt vmcnt(63)
	v_lshlrev_b32_e32 v16, 16, v55
	v_and_b32_e32 v17, 0xffff0000, v55
	v_pk_mul_f32 v[14:15], v[10:11], v[12:13]
	v_pk_fma_f32 v[10:11], v[10:11], v[12:13], v[16:17]
	v_cvt_pk_bf16_f32 v18, v14, v15
	v_mul_f32_e32 v12, 0x3fb8aa3b, v204
	v_mul_f32_e32 v13, 0x3fb8aa3b, v205
	global_store_dword v2, v18, s[16:17]
	s_add_u32 s16, s16, 0x40000
	s_addc_u32 s17, s17, 0
	v_exp_f32_e32 v12, v12
	v_exp_f32_e32 v13, v13
	global_load_dword v55, v2, s[14:15]
	global_load_dwordx2 v[204:205], v4, s[18:19]
	s_add_u32 s14, s14, 0x40000
	s_addc_u32 s15, s15, 0
	s_add_u32 s18, s18, 0x800
	s_addc_u32 s19, s19, 0
	s_waitcnt vmcnt(63)
	v_lshlrev_b32_e32 v16, 16, v56
	v_and_b32_e32 v17, 0xffff0000, v56
	v_pk_mul_f32 v[14:15], v[10:11], v[12:13]
	v_pk_fma_f32 v[10:11], v[10:11], v[12:13], v[16:17]
	v_cvt_pk_bf16_f32 v19, v14, v15
	v_mul_f32_e32 v12, 0x3fb8aa3b, v206
	v_mul_f32_e32 v13, 0x3fb8aa3b, v207
	global_store_dword v2, v19, s[16:17]
	s_add_u32 s16, s16, 0x40000
	s_addc_u32 s17, s17, 0
	v_exp_f32_e32 v12, v12
	v_exp_f32_e32 v13, v13
	global_load_dword v56, v2, s[14:15]
	global_load_dwordx2 v[206:207], v4, s[18:19]
	s_add_u32 s14, s14, 0x40000
	s_addc_u32 s15, s15, 0
	s_add_u32 s18, s18, 0x800
	s_addc_u32 s19, s19, 0
	s_waitcnt vmcnt(63)
	v_lshlrev_b32_e32 v16, 16, v57
	v_and_b32_e32 v17, 0xffff0000, v57
	v_pk_mul_f32 v[14:15], v[10:11], v[12:13]
	v_pk_fma_f32 v[10:11], v[10:11], v[12:13], v[16:17]
	v_cvt_pk_bf16_f32 v22, v14, v15
	v_mul_f32_e32 v12, 0x3fb8aa3b, v208
	v_mul_f32_e32 v13, 0x3fb8aa3b, v209
	global_store_dword v2, v22, s[16:17]
	s_add_u32 s16, s16, 0x40000
	s_addc_u32 s17, s17, 0
	v_exp_f32_e32 v12, v12
	v_exp_f32_e32 v13, v13
	global_load_dword v57, v2, s[14:15]
	global_load_dwordx2 v[208:209], v4, s[18:19]
	s_add_u32 s14, s14, 0x40000
	s_addc_u32 s15, s15, 0
	s_add_u32 s18, s18, 0x800
	s_addc_u32 s19, s19, 0
	s_waitcnt vmcnt(63)
	v_lshlrev_b32_e32 v16, 16, v58
	v_and_b32_e32 v17, 0xffff0000, v58
	v_pk_mul_f32 v[14:15], v[10:11], v[12:13]
	v_pk_fma_f32 v[10:11], v[10:11], v[12:13], v[16:17]
	v_cvt_pk_bf16_f32 v18, v14, v15
	v_mul_f32_e32 v12, 0x3fb8aa3b, v210
	v_mul_f32_e32 v13, 0x3fb8aa3b, v211
	global_store_dword v2, v18, s[16:17]
	s_add_u32 s16, s16, 0x40000
	s_addc_u32 s17, s17, 0
	v_exp_f32_e32 v12, v12
	v_exp_f32_e32 v13, v13
	global_load_dword v58, v2, s[14:15]
	global_load_dwordx2 v[210:211], v4, s[18:19]
	s_add_u32 s14, s14, 0x40000
	s_addc_u32 s15, s15, 0
	s_add_u32 s18, s18, 0x800
	s_addc_u32 s19, s19, 0
	s_waitcnt vmcnt(63)
	v_lshlrev_b32_e32 v16, 16, v59
	v_and_b32_e32 v17, 0xffff0000, v59
	v_pk_mul_f32 v[14:15], v[10:11], v[12:13]
	v_pk_fma_f32 v[10:11], v[10:11], v[12:13], v[16:17]
	v_cvt_pk_bf16_f32 v19, v14, v15
	v_mul_f32_e32 v12, 0x3fb8aa3b, v212
	v_mul_f32_e32 v13, 0x3fb8aa3b, v213
	global_store_dword v2, v19, s[16:17]
	s_add_u32 s16, s16, 0x40000
	s_addc_u32 s17, s17, 0
	v_exp_f32_e32 v12, v12
	v_exp_f32_e32 v13, v13
	global_load_dword v59, v2, s[14:15]
	global_load_dwordx2 v[212:213], v4, s[18:19]
	s_add_u32 s14, s14, 0x40000
	s_addc_u32 s15, s15, 0
	s_add_u32 s18, s18, 0x800
	s_addc_u32 s19, s19, 0
	s_waitcnt vmcnt(63)
	v_lshlrev_b32_e32 v16, 16, v60
	v_and_b32_e32 v17, 0xffff0000, v60
	v_pk_mul_f32 v[14:15], v[10:11], v[12:13]
	v_pk_fma_f32 v[10:11], v[10:11], v[12:13], v[16:17]
	v_cvt_pk_bf16_f32 v22, v14, v15
	v_mul_f32_e32 v12, 0x3fb8aa3b, v214
	v_mul_f32_e32 v13, 0x3fb8aa3b, v215
	global_store_dword v2, v22, s[16:17]
	s_add_u32 s16, s16, 0x40000
	s_addc_u32 s17, s17, 0
	v_exp_f32_e32 v12, v12
	v_exp_f32_e32 v13, v13
	global_load_dword v60, v2, s[14:15]
	global_load_dwordx2 v[214:215], v4, s[18:19]
	s_add_u32 s14, s14, 0x40000
	s_addc_u32 s15, s15, 0
	s_add_u32 s18, s18, 0x800
	s_addc_u32 s19, s19, 0
	s_waitcnt vmcnt(63)
	v_lshlrev_b32_e32 v16, 16, v61
	v_and_b32_e32 v17, 0xffff0000, v61
	v_pk_mul_f32 v[14:15], v[10:11], v[12:13]
	v_pk_fma_f32 v[10:11], v[10:11], v[12:13], v[16:17]
	v_cvt_pk_bf16_f32 v18, v14, v15
	v_mul_f32_e32 v12, 0x3fb8aa3b, v216
	v_mul_f32_e32 v13, 0x3fb8aa3b, v217
	global_store_dword v2, v18, s[16:17]
	s_add_u32 s16, s16, 0x40000
	s_addc_u32 s17, s17, 0
	v_exp_f32_e32 v12, v12
	v_exp_f32_e32 v13, v13
	global_load_dword v61, v2, s[14:15]
	global_load_dwordx2 v[216:217], v4, s[18:19]
	s_add_u32 s14, s14, 0x40000
	s_addc_u32 s15, s15, 0
	s_add_u32 s18, s18, 0x800
	s_addc_u32 s19, s19, 0
	s_waitcnt vmcnt(63)
	v_lshlrev_b32_e32 v16, 16, v27
	v_and_b32_e32 v17, 0xffff0000, v27
	v_pk_mul_f32 v[14:15], v[10:11], v[12:13]
	s_nop 0
	v_pk_add_f32 v[10:11], v[14:15], v[16:17]
	v_cvt_pk_bf16_f32 v19, v14, v15
	v_mul_f32_e32 v12, 0x3fb8aa3b, v134
	v_mul_f32_e32 v13, 0x3fb8aa3b, v135
	global_store_dword v2, v19, s[16:17]
	s_add_u32 s16, s16, 0x40000
	s_addc_u32 s17, s17, 0
	v_exp_f32_e32 v12, v12
	v_exp_f32_e32 v13, v13
	global_load_dword v27, v2, s[14:15]
	global_load_dwordx2 v[134:135], v4, s[18:19]
	s_add_u32 s14, s14, 0x40000
	s_addc_u32 s15, s15, 0
	s_add_u32 s18, s18, 0x800
	s_addc_u32 s19, s19, 0
	s_waitcnt vmcnt(63)
	v_lshlrev_b32_e32 v16, 16, v28
	v_and_b32_e32 v17, 0xffff0000, v28
	v_pk_mul_f32 v[14:15], v[10:11], v[12:13]
	v_pk_fma_f32 v[10:11], v[10:11], v[12:13], v[16:17]
	v_cvt_pk_bf16_f32 v22, v14, v15
	v_mul_f32_e32 v12, 0x3fb8aa3b, v136
	v_mul_f32_e32 v13, 0x3fb8aa3b, v137
	global_store_dword v2, v22, s[16:17]
	s_add_u32 s16, s16, 0x40000
	s_addc_u32 s17, s17, 0
	v_exp_f32_e32 v12, v12
	v_exp_f32_e32 v13, v13
	global_load_dword v28, v2, s[14:15]
	global_load_dwordx2 v[136:137], v4, s[18:19]
	s_add_u32 s14, s14, 0x40000
	s_addc_u32 s15, s15, 0
	s_add_u32 s18, s18, 0x800
	s_addc_u32 s19, s19, 0
	s_waitcnt vmcnt(63)
	v_lshlrev_b32_e32 v16, 16, v29
	v_and_b32_e32 v17, 0xffff0000, v29
	v_pk_mul_f32 v[14:15], v[10:11], v[12:13]
	v_pk_fma_f32 v[10:11], v[10:11], v[12:13], v[16:17]
	v_cvt_pk_bf16_f32 v18, v14, v15
	v_mul_f32_e32 v12, 0x3fb8aa3b, v138
	v_mul_f32_e32 v13, 0x3fb8aa3b, v139
	global_store_dword v2, v18, s[16:17]
	s_add_u32 s16, s16, 0x40000
	s_addc_u32 s17, s17, 0
	v_exp_f32_e32 v12, v12
	v_exp_f32_e32 v13, v13
	global_load_dword v29, v2, s[14:15]
	global_load_dwordx2 v[138:139], v4, s[18:19]
	s_add_u32 s14, s14, 0x40000
	s_addc_u32 s15, s15, 0
	s_add_u32 s18, s18, 0x800
	s_addc_u32 s19, s19, 0
	s_waitcnt vmcnt(63)
	v_lshlrev_b32_e32 v16, 16, v30
	v_and_b32_e32 v17, 0xffff0000, v30
	v_pk_mul_f32 v[14:15], v[10:11], v[12:13]
	v_pk_fma_f32 v[10:11], v[10:11], v[12:13], v[16:17]
	v_cvt_pk_bf16_f32 v19, v14, v15
	v_mul_f32_e32 v12, 0x3fb8aa3b, v140
	v_mul_f32_e32 v13, 0x3fb8aa3b, v141
	global_store_dword v2, v19, s[16:17]
	s_add_u32 s16, s16, 0x40000
	s_addc_u32 s17, s17, 0
	v_exp_f32_e32 v12, v12
	v_exp_f32_e32 v13, v13
	global_load_dword v30, v2, s[14:15]
	global_load_dwordx2 v[140:141], v4, s[18:19]
	s_add_u32 s14, s14, 0x40000
	s_addc_u32 s15, s15, 0
	s_add_u32 s18, s18, 0x800
	s_addc_u32 s19, s19, 0
	s_waitcnt vmcnt(63)
	v_lshlrev_b32_e32 v16, 16, v31
	v_and_b32_e32 v17, 0xffff0000, v31
	v_pk_mul_f32 v[14:15], v[10:11], v[12:13]
	v_pk_fma_f32 v[10:11], v[10:11], v[12:13], v[16:17]
	v_cvt_pk_bf16_f32 v22, v14, v15
	v_mul_f32_e32 v12, 0x3fb8aa3b, v142
	v_mul_f32_e32 v13, 0x3fb8aa3b, v143
	global_store_dword v2, v22, s[16:17]
	s_add_u32 s16, s16, 0x40000
	s_addc_u32 s17, s17, 0
	v_exp_f32_e32 v12, v12
	v_exp_f32_e32 v13, v13
	global_load_dword v31, v2, s[14:15]
	global_load_dwordx2 v[142:143], v4, s[18:19]
	s_add_u32 s14, s14, 0x40000
	s_addc_u32 s15, s15, 0
	s_add_u32 s18, s18, 0x800
	s_addc_u32 s19, s19, 0
	s_waitcnt vmcnt(63)
	v_lshlrev_b32_e32 v16, 16, v32
	v_and_b32_e32 v17, 0xffff0000, v32
	v_pk_mul_f32 v[14:15], v[10:11], v[12:13]
	v_pk_fma_f32 v[10:11], v[10:11], v[12:13], v[16:17]
	v_cvt_pk_bf16_f32 v18, v14, v15
	v_mul_f32_e32 v12, 0x3fb8aa3b, v144
	v_mul_f32_e32 v13, 0x3fb8aa3b, v145
	global_store_dword v2, v18, s[16:17]
	s_add_u32 s16, s16, 0x40000
	s_addc_u32 s17, s17, 0
	v_exp_f32_e32 v12, v12
	v_exp_f32_e32 v13, v13
	global_load_dword v32, v2, s[14:15]
	global_load_dwordx2 v[144:145], v4, s[18:19]
	s_add_u32 s14, s14, 0x40000
	s_addc_u32 s15, s15, 0
	s_add_u32 s18, s18, 0x800
	s_addc_u32 s19, s19, 0
	s_waitcnt vmcnt(63)
	v_lshlrev_b32_e32 v16, 16, v33
	v_and_b32_e32 v17, 0xffff0000, v33
	v_pk_mul_f32 v[14:15], v[10:11], v[12:13]
	v_pk_fma_f32 v[10:11], v[10:11], v[12:13], v[16:17]
	v_cvt_pk_bf16_f32 v19, v14, v15
	v_mul_f32_e32 v12, 0x3fb8aa3b, v146
	v_mul_f32_e32 v13, 0x3fb8aa3b, v147
	global_store_dword v2, v19, s[16:17]
	s_add_u32 s16, s16, 0x40000
	s_addc_u32 s17, s17, 0
	v_exp_f32_e32 v12, v12
	v_exp_f32_e32 v13, v13
	global_load_dword v33, v2, s[14:15]
	global_load_dwordx2 v[146:147], v4, s[18:19]
	s_add_u32 s14, s14, 0x40000
	s_addc_u32 s15, s15, 0
	s_add_u32 s18, s18, 0x800
	s_addc_u32 s19, s19, 0
	s_waitcnt vmcnt(63)
	v_lshlrev_b32_e32 v16, 16, v34
	v_and_b32_e32 v17, 0xffff0000, v34
	v_pk_mul_f32 v[14:15], v[10:11], v[12:13]
	v_pk_fma_f32 v[10:11], v[10:11], v[12:13], v[16:17]
	v_cvt_pk_bf16_f32 v22, v14, v15
	v_mul_f32_e32 v12, 0x3fb8aa3b, v148
	v_mul_f32_e32 v13, 0x3fb8aa3b, v149
	global_store_dword v2, v22, s[16:17]
	s_add_u32 s16, s16, 0x40000
	s_addc_u32 s17, s17, 0
	v_exp_f32_e32 v12, v12
	v_exp_f32_e32 v13, v13
	global_load_dword v34, v2, s[14:15]
	global_load_dwordx2 v[148:149], v4, s[18:19]
	s_add_u32 s14, s14, 0x40000
	s_addc_u32 s15, s15, 0
	s_add_u32 s18, s18, 0x800
	s_addc_u32 s19, s19, 0
	s_waitcnt vmcnt(63)
	v_lshlrev_b32_e32 v16, 16, v35
	v_and_b32_e32 v17, 0xffff0000, v35
	v_pk_mul_f32 v[14:15], v[10:11], v[12:13]
	v_pk_fma_f32 v[10:11], v[10:11], v[12:13], v[16:17]
	v_cvt_pk_bf16_f32 v18, v14, v15
	v_mul_f32_e32 v12, 0x3fb8aa3b, v150
	v_mul_f32_e32 v13, 0x3fb8aa3b, v151
	global_store_dword v2, v18, s[16:17]
	s_add_u32 s16, s16, 0x40000
	s_addc_u32 s17, s17, 0
	v_exp_f32_e32 v12, v12
	v_exp_f32_e32 v13, v13
	global_load_dword v35, v2, s[14:15]
	global_load_dwordx2 v[150:151], v4, s[18:19]
	s_add_u32 s14, s14, 0x40000
	s_addc_u32 s15, s15, 0
	s_add_u32 s18, s18, 0x800
	s_addc_u32 s19, s19, 0
	s_waitcnt vmcnt(63)
	v_lshlrev_b32_e32 v16, 16, v36
	v_and_b32_e32 v17, 0xffff0000, v36
	v_pk_mul_f32 v[14:15], v[10:11], v[12:13]
	v_pk_fma_f32 v[10:11], v[10:11], v[12:13], v[16:17]
	v_cvt_pk_bf16_f32 v19, v14, v15
	v_mul_f32_e32 v12, 0x3fb8aa3b, v152
	v_mul_f32_e32 v13, 0x3fb8aa3b, v153
	global_store_dword v2, v19, s[16:17]
	s_add_u32 s16, s16, 0x40000
	s_addc_u32 s17, s17, 0
	v_exp_f32_e32 v12, v12
	v_exp_f32_e32 v13, v13
	global_load_dword v36, v2, s[14:15]
	global_load_dwordx2 v[152:153], v4, s[18:19]
	s_add_u32 s14, s14, 0x40000
	s_addc_u32 s15, s15, 0
	s_add_u32 s18, s18, 0x800
	s_addc_u32 s19, s19, 0
	s_waitcnt vmcnt(63)
	v_lshlrev_b32_e32 v16, 16, v37
	v_and_b32_e32 v17, 0xffff0000, v37
	v_pk_mul_f32 v[14:15], v[10:11], v[12:13]
	v_pk_fma_f32 v[10:11], v[10:11], v[12:13], v[16:17]
	v_cvt_pk_bf16_f32 v22, v14, v15
	v_mul_f32_e32 v12, 0x3fb8aa3b, v154
	v_mul_f32_e32 v13, 0x3fb8aa3b, v155
	global_store_dword v2, v22, s[16:17]
	s_add_u32 s16, s16, 0x40000
	s_addc_u32 s17, s17, 0
	v_exp_f32_e32 v12, v12
	v_exp_f32_e32 v13, v13
	global_load_dword v37, v2, s[14:15]
	global_load_dwordx2 v[154:155], v4, s[18:19]
	s_add_u32 s14, s14, 0x40000
	s_addc_u32 s15, s15, 0
	s_add_u32 s18, s18, 0x800
	s_addc_u32 s19, s19, 0
	s_waitcnt vmcnt(63)
	v_lshlrev_b32_e32 v16, 16, v38
	v_and_b32_e32 v17, 0xffff0000, v38
	v_pk_mul_f32 v[14:15], v[10:11], v[12:13]
	v_pk_fma_f32 v[10:11], v[10:11], v[12:13], v[16:17]
	v_cvt_pk_bf16_f32 v18, v14, v15
	v_mul_f32_e32 v12, 0x3fb8aa3b, v170
	v_mul_f32_e32 v13, 0x3fb8aa3b, v171
	global_store_dword v2, v18, s[16:17]
	s_add_u32 s16, s16, 0x40000
	s_addc_u32 s17, s17, 0
	v_exp_f32_e32 v12, v12
	v_exp_f32_e32 v13, v13
	global_load_dword v38, v2, s[14:15]
	global_load_dwordx2 v[170:171], v4, s[18:19]
	s_add_u32 s14, s14, 0x40000
	s_addc_u32 s15, s15, 0
	s_add_u32 s18, s18, 0x800
	s_addc_u32 s19, s19, 0
	s_waitcnt vmcnt(63)
	v_lshlrev_b32_e32 v16, 16, v39
	v_and_b32_e32 v17, 0xffff0000, v39
	v_pk_mul_f32 v[14:15], v[10:11], v[12:13]
	v_pk_fma_f32 v[10:11], v[10:11], v[12:13], v[16:17]
	v_cvt_pk_bf16_f32 v19, v14, v15
	v_mul_f32_e32 v12, 0x3fb8aa3b, v172
	v_mul_f32_e32 v13, 0x3fb8aa3b, v173
	global_store_dword v2, v19, s[16:17]
	s_add_u32 s16, s16, 0x40000
	s_addc_u32 s17, s17, 0
	v_exp_f32_e32 v12, v12
	v_exp_f32_e32 v13, v13
	global_load_dword v39, v2, s[14:15]
	global_load_dwordx2 v[172:173], v4, s[18:19]
	s_add_u32 s14, s14, 0x40000
	s_addc_u32 s15, s15, 0
	s_add_u32 s18, s18, 0x800
	s_addc_u32 s19, s19, 0
	s_waitcnt vmcnt(63)
	v_lshlrev_b32_e32 v16, 16, v40
	v_and_b32_e32 v17, 0xffff0000, v40
	v_pk_mul_f32 v[14:15], v[10:11], v[12:13]
	v_pk_fma_f32 v[10:11], v[10:11], v[12:13], v[16:17]
	v_cvt_pk_bf16_f32 v22, v14, v15
	v_mul_f32_e32 v12, 0x3fb8aa3b, v174
	v_mul_f32_e32 v13, 0x3fb8aa3b, v175
	global_store_dword v2, v22, s[16:17]
	s_add_u32 s16, s16, 0x40000
	s_addc_u32 s17, s17, 0
	v_exp_f32_e32 v12, v12
	v_exp_f32_e32 v13, v13
	global_load_dword v40, v2, s[14:15]
	global_load_dwordx2 v[174:175], v4, s[18:19]
	s_add_u32 s14, s14, 0x40000
	s_addc_u32 s15, s15, 0
	s_add_u32 s18, s18, 0x800
	s_addc_u32 s19, s19, 0
	s_waitcnt vmcnt(63)
	v_lshlrev_b32_e32 v16, 16, v41
	v_and_b32_e32 v17, 0xffff0000, v41
	v_pk_mul_f32 v[14:15], v[10:11], v[12:13]
	v_pk_fma_f32 v[10:11], v[10:11], v[12:13], v[16:17]
	v_cvt_pk_bf16_f32 v18, v14, v15
	v_mul_f32_e32 v12, 0x3fb8aa3b, v176
	v_mul_f32_e32 v13, 0x3fb8aa3b, v177
	global_store_dword v2, v18, s[16:17]
	s_add_u32 s16, s16, 0x40000
	s_addc_u32 s17, s17, 0
	v_exp_f32_e32 v12, v12
	v_exp_f32_e32 v13, v13
	global_load_dword v41, v2, s[14:15]
	global_load_dwordx2 v[176:177], v4, s[18:19]
	s_add_u32 s14, s14, 0x40000
	s_addc_u32 s15, s15, 0
	s_add_u32 s18, s18, 0x800
	s_addc_u32 s19, s19, 0
	s_waitcnt vmcnt(63)
	v_lshlrev_b32_e32 v16, 16, v42
	v_and_b32_e32 v17, 0xffff0000, v42
	v_pk_mul_f32 v[14:15], v[10:11], v[12:13]
	v_pk_fma_f32 v[10:11], v[10:11], v[12:13], v[16:17]
	v_cvt_pk_bf16_f32 v19, v14, v15
	v_mul_f32_e32 v12, 0x3fb8aa3b, v178
	v_mul_f32_e32 v13, 0x3fb8aa3b, v179
	global_store_dword v2, v19, s[16:17]
	s_add_u32 s16, s16, 0x40000
	s_addc_u32 s17, s17, 0
	v_exp_f32_e32 v12, v12
	v_exp_f32_e32 v13, v13
	global_load_dword v42, v2, s[14:15]
	global_load_dwordx2 v[178:179], v4, s[18:19]
	s_add_u32 s14, s14, 0x40000
	s_addc_u32 s15, s15, 0
	s_add_u32 s18, s18, 0x800
	s_addc_u32 s19, s19, 0
	s_waitcnt vmcnt(63)
	v_lshlrev_b32_e32 v16, 16, v43
	v_and_b32_e32 v17, 0xffff0000, v43
	v_pk_mul_f32 v[14:15], v[10:11], v[12:13]
	v_pk_fma_f32 v[10:11], v[10:11], v[12:13], v[16:17]
	v_cvt_pk_bf16_f32 v22, v14, v15
	v_mul_f32_e32 v12, 0x3fb8aa3b, v180
	v_mul_f32_e32 v13, 0x3fb8aa3b, v181
	global_store_dword v2, v22, s[16:17]
	s_add_u32 s16, s16, 0x40000
	s_addc_u32 s17, s17, 0
	v_exp_f32_e32 v12, v12
	v_exp_f32_e32 v13, v13
	global_load_dword v43, v2, s[14:15]
	global_load_dwordx2 v[180:181], v4, s[18:19]
	s_add_u32 s14, s14, 0x40000
	s_addc_u32 s15, s15, 0
	s_add_u32 s18, s18, 0x800
	s_addc_u32 s19, s19, 0
	s_waitcnt vmcnt(63)
	v_lshlrev_b32_e32 v16, 16, v44
	v_and_b32_e32 v17, 0xffff0000, v44
	v_pk_mul_f32 v[14:15], v[10:11], v[12:13]
	v_pk_fma_f32 v[10:11], v[10:11], v[12:13], v[16:17]
	v_cvt_pk_bf16_f32 v18, v14, v15
	v_mul_f32_e32 v12, 0x3fb8aa3b, v182
	v_mul_f32_e32 v13, 0x3fb8aa3b, v183
	global_store_dword v2, v18, s[16:17]
	s_add_u32 s16, s16, 0x40000
	s_addc_u32 s17, s17, 0
	v_exp_f32_e32 v12, v12
	v_exp_f32_e32 v13, v13
	global_load_dword v44, v2, s[14:15]
	global_load_dwordx2 v[182:183], v4, s[18:19]
	s_add_u32 s14, s14, 0x40000
	s_addc_u32 s15, s15, 0
	s_add_u32 s18, s18, 0x800
	s_addc_u32 s19, s19, 0
	s_waitcnt vmcnt(63)
	v_lshlrev_b32_e32 v16, 16, v45
	v_and_b32_e32 v17, 0xffff0000, v45
	v_pk_mul_f32 v[14:15], v[10:11], v[12:13]
	v_pk_fma_f32 v[10:11], v[10:11], v[12:13], v[16:17]
	v_cvt_pk_bf16_f32 v19, v14, v15
	v_mul_f32_e32 v12, 0x3fb8aa3b, v188
	v_mul_f32_e32 v13, 0x3fb8aa3b, v189
	global_store_dword v2, v19, s[16:17]
	s_add_u32 s16, s16, 0x40000
	s_addc_u32 s17, s17, 0
	v_exp_f32_e32 v12, v12
	v_exp_f32_e32 v13, v13
	global_load_dword v45, v2, s[14:15]
	global_load_dwordx2 v[188:189], v4, s[18:19]
	s_add_u32 s14, s14, 0x40000
	s_addc_u32 s15, s15, 0
	s_add_u32 s18, s18, 0x800
	s_addc_u32 s19, s19, 0
	s_waitcnt vmcnt(63)
	v_lshlrev_b32_e32 v16, 16, v46
	v_and_b32_e32 v17, 0xffff0000, v46
	v_pk_mul_f32 v[14:15], v[10:11], v[12:13]
	v_pk_fma_f32 v[10:11], v[10:11], v[12:13], v[16:17]
	v_cvt_pk_bf16_f32 v22, v14, v15
	v_mul_f32_e32 v12, 0x3fb8aa3b, v190
	v_mul_f32_e32 v13, 0x3fb8aa3b, v191
	global_store_dword v2, v22, s[16:17]
	s_add_u32 s16, s16, 0x40000
	s_addc_u32 s17, s17, 0
	v_exp_f32_e32 v12, v12
	v_exp_f32_e32 v13, v13
	global_load_dword v46, v2, s[14:15]
	global_load_dwordx2 v[190:191], v4, s[18:19]
	s_add_u32 s14, s14, 0x40000
	s_addc_u32 s15, s15, 0
	s_add_u32 s18, s18, 0x800
	s_addc_u32 s19, s19, 0
	s_waitcnt vmcnt(63)
	v_lshlrev_b32_e32 v16, 16, v50
	v_and_b32_e32 v17, 0xffff0000, v50
	v_pk_mul_f32 v[14:15], v[10:11], v[12:13]
	v_pk_fma_f32 v[10:11], v[10:11], v[12:13], v[16:17]
	v_cvt_pk_bf16_f32 v18, v14, v15
	v_mul_f32_e32 v12, 0x3fb8aa3b, v192
	v_mul_f32_e32 v13, 0x3fb8aa3b, v193
	global_store_dword v2, v18, s[16:17]
	s_add_u32 s16, s16, 0x40000
	s_addc_u32 s17, s17, 0
	v_exp_f32_e32 v12, v12
	v_exp_f32_e32 v13, v13
	global_load_dword v50, v2, s[14:15]
	global_load_dwordx2 v[192:193], v4, s[18:19]
	s_add_u32 s14, s14, 0x40000
	s_addc_u32 s15, s15, 0
	s_add_u32 s18, s18, 0x800
	s_addc_u32 s19, s19, 0
	s_waitcnt vmcnt(63)
	v_lshlrev_b32_e32 v16, 16, v51
	v_and_b32_e32 v17, 0xffff0000, v51
	v_pk_mul_f32 v[14:15], v[10:11], v[12:13]
	v_pk_fma_f32 v[10:11], v[10:11], v[12:13], v[16:17]
	v_cvt_pk_bf16_f32 v19, v14, v15
	v_mul_f32_e32 v12, 0x3fb8aa3b, v194
	v_mul_f32_e32 v13, 0x3fb8aa3b, v195
	global_store_dword v2, v19, s[16:17]
	s_add_u32 s16, s16, 0x40000
	s_addc_u32 s17, s17, 0
	v_exp_f32_e32 v12, v12
	v_exp_f32_e32 v13, v13
	global_load_dword v51, v2, s[14:15]
	global_load_dwordx2 v[194:195], v4, s[18:19]
	s_add_u32 s14, s14, 0x40000
	s_addc_u32 s15, s15, 0
	s_add_u32 s18, s18, 0x800
	s_addc_u32 s19, s19, 0
	s_waitcnt vmcnt(63)
	v_lshlrev_b32_e32 v16, 16, v52
	v_and_b32_e32 v17, 0xffff0000, v52
	v_pk_mul_f32 v[14:15], v[10:11], v[12:13]
	v_pk_fma_f32 v[10:11], v[10:11], v[12:13], v[16:17]
	v_cvt_pk_bf16_f32 v22, v14, v15
	v_mul_f32_e32 v12, 0x3fb8aa3b, v196
	v_mul_f32_e32 v13, 0x3fb8aa3b, v197
	global_store_dword v2, v22, s[16:17]
	s_add_u32 s16, s16, 0x40000
	s_addc_u32 s17, s17, 0
	v_exp_f32_e32 v12, v12
	v_exp_f32_e32 v13, v13
	global_load_dword v52, v2, s[14:15]
	global_load_dwordx2 v[196:197], v4, s[18:19]
	s_add_u32 s14, s14, 0x40000
	s_addc_u32 s15, s15, 0
	s_add_u32 s18, s18, 0x800
	s_addc_u32 s19, s19, 0
	s_waitcnt vmcnt(63)
	v_lshlrev_b32_e32 v16, 16, v53
	v_and_b32_e32 v17, 0xffff0000, v53
	v_pk_mul_f32 v[14:15], v[10:11], v[12:13]
	v_pk_fma_f32 v[10:11], v[10:11], v[12:13], v[16:17]
	v_cvt_pk_bf16_f32 v18, v14, v15
	v_mul_f32_e32 v12, 0x3fb8aa3b, v198
	v_mul_f32_e32 v13, 0x3fb8aa3b, v199
	global_store_dword v2, v18, s[16:17]
	s_add_u32 s16, s16, 0x40000
	s_addc_u32 s17, s17, 0
	v_exp_f32_e32 v12, v12
	v_exp_f32_e32 v13, v13
	global_load_dword v53, v2, s[14:15]
	global_load_dwordx2 v[198:199], v4, s[18:19]
	s_add_u32 s14, s14, 0x40000
	s_addc_u32 s15, s15, 0
	s_add_u32 s18, s18, 0x800
	s_addc_u32 s19, s19, 0
	s_waitcnt vmcnt(63)
	v_lshlrev_b32_e32 v16, 16, v54
	v_and_b32_e32 v17, 0xffff0000, v54
	v_pk_mul_f32 v[14:15], v[10:11], v[12:13]
	v_pk_fma_f32 v[10:11], v[10:11], v[12:13], v[16:17]
	v_cvt_pk_bf16_f32 v19, v14, v15
	v_mul_f32_e32 v12, 0x3fb8aa3b, v202
	v_mul_f32_e32 v13, 0x3fb8aa3b, v203
	global_store_dword v2, v19, s[16:17]
	s_add_u32 s16, s16, 0x40000
	s_addc_u32 s17, s17, 0
	v_exp_f32_e32 v12, v12
	v_exp_f32_e32 v13, v13
	global_load_dword v54, v2, s[14:15]
	global_load_dwordx2 v[202:203], v4, s[18:19]
	s_add_u32 s14, s14, 0x40000
	s_addc_u32 s15, s15, 0
	s_add_u32 s18, s18, 0x800
	s_addc_u32 s19, s19, 0
	s_waitcnt vmcnt(63)
	v_lshlrev_b32_e32 v16, 16, v55
	v_and_b32_e32 v17, 0xffff0000, v55
	v_pk_mul_f32 v[14:15], v[10:11], v[12:13]
	v_pk_fma_f32 v[10:11], v[10:11], v[12:13], v[16:17]
	v_cvt_pk_bf16_f32 v22, v14, v15
	v_mul_f32_e32 v12, 0x3fb8aa3b, v204
	v_mul_f32_e32 v13, 0x3fb8aa3b, v205
	global_store_dword v2, v22, s[16:17]
	s_add_u32 s16, s16, 0x40000
	s_addc_u32 s17, s17, 0
	v_exp_f32_e32 v12, v12
	v_exp_f32_e32 v13, v13
	global_load_dword v55, v2, s[14:15]
	global_load_dwordx2 v[204:205], v4, s[18:19]
	s_add_u32 s14, s14, 0x40000
	s_addc_u32 s15, s15, 0
	s_add_u32 s18, s18, 0x800
	s_addc_u32 s19, s19, 0
	s_waitcnt vmcnt(63)
	v_lshlrev_b32_e32 v16, 16, v56
	v_and_b32_e32 v17, 0xffff0000, v56
	v_pk_mul_f32 v[14:15], v[10:11], v[12:13]
	v_pk_fma_f32 v[10:11], v[10:11], v[12:13], v[16:17]
	v_cvt_pk_bf16_f32 v18, v14, v15
	v_mul_f32_e32 v12, 0x3fb8aa3b, v206
	v_mul_f32_e32 v13, 0x3fb8aa3b, v207
	global_store_dword v2, v18, s[16:17]
	s_add_u32 s16, s16, 0x40000
	s_addc_u32 s17, s17, 0
	v_exp_f32_e32 v12, v12
	v_exp_f32_e32 v13, v13
	global_load_dword v56, v2, s[14:15]
	global_load_dwordx2 v[206:207], v4, s[18:19]
	s_add_u32 s14, s14, 0x40000
	s_addc_u32 s15, s15, 0
	s_add_u32 s18, s18, 0x800
	s_addc_u32 s19, s19, 0
	s_waitcnt vmcnt(63)
	v_lshlrev_b32_e32 v16, 16, v57
	v_and_b32_e32 v17, 0xffff0000, v57
	v_pk_mul_f32 v[14:15], v[10:11], v[12:13]
	v_pk_fma_f32 v[10:11], v[10:11], v[12:13], v[16:17]
	v_cvt_pk_bf16_f32 v19, v14, v15
	v_mul_f32_e32 v12, 0x3fb8aa3b, v208
	v_mul_f32_e32 v13, 0x3fb8aa3b, v209
	global_store_dword v2, v19, s[16:17]
	s_add_u32 s16, s16, 0x40000
	s_addc_u32 s17, s17, 0
	v_exp_f32_e32 v12, v12
	v_exp_f32_e32 v13, v13
	global_load_dword v57, v2, s[14:15]
	global_load_dwordx2 v[208:209], v4, s[18:19]
	s_add_u32 s14, s14, 0x40000
	s_addc_u32 s15, s15, 0
	s_add_u32 s18, s18, 0x800
	s_addc_u32 s19, s19, 0
	s_waitcnt vmcnt(63)
	v_lshlrev_b32_e32 v16, 16, v58
	v_and_b32_e32 v17, 0xffff0000, v58
	v_pk_mul_f32 v[14:15], v[10:11], v[12:13]
	v_pk_fma_f32 v[10:11], v[10:11], v[12:13], v[16:17]
	v_cvt_pk_bf16_f32 v22, v14, v15
	v_mul_f32_e32 v12, 0x3fb8aa3b, v210
	v_mul_f32_e32 v13, 0x3fb8aa3b, v211
	global_store_dword v2, v22, s[16:17]
	s_add_u32 s16, s16, 0x40000
	s_addc_u32 s17, s17, 0
	v_exp_f32_e32 v12, v12
	v_exp_f32_e32 v13, v13
	global_load_dword v58, v2, s[14:15]
	global_load_dwordx2 v[210:211], v4, s[18:19]
	s_add_u32 s14, s14, 0x40000
	s_addc_u32 s15, s15, 0
	s_add_u32 s18, s18, 0x800
	s_addc_u32 s19, s19, 0
	s_waitcnt vmcnt(63)
	v_lshlrev_b32_e32 v16, 16, v59
	v_and_b32_e32 v17, 0xffff0000, v59
	v_pk_mul_f32 v[14:15], v[10:11], v[12:13]
	v_pk_fma_f32 v[10:11], v[10:11], v[12:13], v[16:17]
	v_cvt_pk_bf16_f32 v18, v14, v15
	v_mul_f32_e32 v12, 0x3fb8aa3b, v212
	v_mul_f32_e32 v13, 0x3fb8aa3b, v213
	global_store_dword v2, v18, s[16:17]
	s_add_u32 s16, s16, 0x40000
	s_addc_u32 s17, s17, 0
	v_exp_f32_e32 v12, v12
	v_exp_f32_e32 v13, v13
	global_load_dword v59, v2, s[14:15]
	global_load_dwordx2 v[212:213], v4, s[18:19]
	s_add_u32 s14, s14, 0x40000
	s_addc_u32 s15, s15, 0
	s_add_u32 s18, s18, 0x800
	s_addc_u32 s19, s19, 0
	s_waitcnt vmcnt(63)
	v_lshlrev_b32_e32 v16, 16, v60
	v_and_b32_e32 v17, 0xffff0000, v60
	v_pk_mul_f32 v[14:15], v[10:11], v[12:13]
	v_pk_fma_f32 v[10:11], v[10:11], v[12:13], v[16:17]
	v_cvt_pk_bf16_f32 v19, v14, v15
	v_mul_f32_e32 v12, 0x3fb8aa3b, v214
	v_mul_f32_e32 v13, 0x3fb8aa3b, v215
	global_store_dword v2, v19, s[16:17]
	s_add_u32 s16, s16, 0x40000
	s_addc_u32 s17, s17, 0
	v_exp_f32_e32 v12, v12
	v_exp_f32_e32 v13, v13
	global_load_dword v60, v2, s[14:15]
	global_load_dwordx2 v[214:215], v4, s[18:19]
	s_add_u32 s14, s14, 0x40000
	s_addc_u32 s15, s15, 0
	s_add_u32 s18, s18, 0x800
	s_addc_u32 s19, s19, 0
	s_waitcnt vmcnt(63)
	v_lshlrev_b32_e32 v16, 16, v61
	v_and_b32_e32 v17, 0xffff0000, v61
	v_pk_mul_f32 v[14:15], v[10:11], v[12:13]
	v_pk_fma_f32 v[10:11], v[10:11], v[12:13], v[16:17]
	v_cvt_pk_bf16_f32 v22, v14, v15
	v_mul_f32_e32 v12, 0x3fb8aa3b, v216
	v_mul_f32_e32 v13, 0x3fb8aa3b, v217
	global_store_dword v2, v22, s[16:17]
	s_add_u32 s16, s16, 0x40000
	s_addc_u32 s17, s17, 0
	v_exp_f32_e32 v12, v12
	v_exp_f32_e32 v13, v13
	global_load_dword v61, v2, s[14:15]
	global_load_dwordx2 v[216:217], v4, s[18:19]
	s_add_u32 s14, s14, 0x40000
	s_addc_u32 s15, s15, 0
	s_add_u32 s18, s18, 0x800
	s_addc_u32 s19, s19, 0
	s_waitcnt vmcnt(63)
	v_lshlrev_b32_e32 v16, 16, v27
	v_and_b32_e32 v17, 0xffff0000, v27
	v_pk_mul_f32 v[14:15], v[10:11], v[12:13]
	s_nop 0
	v_pk_add_f32 v[10:11], v[14:15], v[16:17]
	v_cvt_pk_bf16_f32 v18, v14, v15
	v_mul_f32_e32 v12, 0x3fb8aa3b, v134
	v_mul_f32_e32 v13, 0x3fb8aa3b, v135
	global_store_dword v2, v18, s[16:17]
	s_add_u32 s16, s16, 0x40000
	s_addc_u32 s17, s17, 0
	v_exp_f32_e32 v12, v12
	v_exp_f32_e32 v13, v13
	s_waitcnt vmcnt(63)
	v_lshlrev_b32_e32 v16, 16, v28
	v_and_b32_e32 v17, 0xffff0000, v28
	v_pk_mul_f32 v[14:15], v[10:11], v[12:13]
	v_pk_fma_f32 v[10:11], v[10:11], v[12:13], v[16:17]
	v_cvt_pk_bf16_f32 v19, v14, v15
	v_mul_f32_e32 v12, 0x3fb8aa3b, v136
	v_mul_f32_e32 v13, 0x3fb8aa3b, v137
	global_store_dword v2, v19, s[16:17]
	s_add_u32 s16, s16, 0x40000
	s_addc_u32 s17, s17, 0
	v_exp_f32_e32 v12, v12
	v_exp_f32_e32 v13, v13
	s_waitcnt vmcnt(63)
	v_lshlrev_b32_e32 v16, 16, v29
	v_and_b32_e32 v17, 0xffff0000, v29
	v_pk_mul_f32 v[14:15], v[10:11], v[12:13]
	v_pk_fma_f32 v[10:11], v[10:11], v[12:13], v[16:17]
	v_cvt_pk_bf16_f32 v22, v14, v15
	v_mul_f32_e32 v12, 0x3fb8aa3b, v138
	v_mul_f32_e32 v13, 0x3fb8aa3b, v139
	global_store_dword v2, v22, s[16:17]
	s_add_u32 s16, s16, 0x40000
	s_addc_u32 s17, s17, 0
	v_exp_f32_e32 v12, v12
	v_exp_f32_e32 v13, v13
	s_waitcnt vmcnt(63)
	v_lshlrev_b32_e32 v16, 16, v30
	v_and_b32_e32 v17, 0xffff0000, v30
	v_pk_mul_f32 v[14:15], v[10:11], v[12:13]
	v_pk_fma_f32 v[10:11], v[10:11], v[12:13], v[16:17]
	v_cvt_pk_bf16_f32 v18, v14, v15
	v_mul_f32_e32 v12, 0x3fb8aa3b, v140
	v_mul_f32_e32 v13, 0x3fb8aa3b, v141
	global_store_dword v2, v18, s[16:17]
	s_add_u32 s16, s16, 0x40000
	s_addc_u32 s17, s17, 0
	v_exp_f32_e32 v12, v12
	v_exp_f32_e32 v13, v13
	s_waitcnt vmcnt(63)
	v_lshlrev_b32_e32 v16, 16, v31
	v_and_b32_e32 v17, 0xffff0000, v31
	v_pk_mul_f32 v[14:15], v[10:11], v[12:13]
	v_pk_fma_f32 v[10:11], v[10:11], v[12:13], v[16:17]
	v_cvt_pk_bf16_f32 v19, v14, v15
	v_mul_f32_e32 v12, 0x3fb8aa3b, v142
	v_mul_f32_e32 v13, 0x3fb8aa3b, v143
	global_store_dword v2, v19, s[16:17]
	s_add_u32 s16, s16, 0x40000
	s_addc_u32 s17, s17, 0
	v_exp_f32_e32 v12, v12
	v_exp_f32_e32 v13, v13
	s_waitcnt vmcnt(63)
	v_lshlrev_b32_e32 v16, 16, v32
	v_and_b32_e32 v17, 0xffff0000, v32
	v_pk_mul_f32 v[14:15], v[10:11], v[12:13]
	v_pk_fma_f32 v[10:11], v[10:11], v[12:13], v[16:17]
	v_cvt_pk_bf16_f32 v22, v14, v15
	v_mul_f32_e32 v12, 0x3fb8aa3b, v144
	v_mul_f32_e32 v13, 0x3fb8aa3b, v145
	global_store_dword v2, v22, s[16:17]
	s_add_u32 s16, s16, 0x40000
	s_addc_u32 s17, s17, 0
	v_exp_f32_e32 v12, v12
	v_exp_f32_e32 v13, v13
	s_waitcnt vmcnt(63)
	v_lshlrev_b32_e32 v16, 16, v33
	v_and_b32_e32 v17, 0xffff0000, v33
	v_pk_mul_f32 v[14:15], v[10:11], v[12:13]
	v_pk_fma_f32 v[10:11], v[10:11], v[12:13], v[16:17]
	v_cvt_pk_bf16_f32 v18, v14, v15
	v_mul_f32_e32 v12, 0x3fb8aa3b, v146
	v_mul_f32_e32 v13, 0x3fb8aa3b, v147
	global_store_dword v2, v18, s[16:17]
	s_add_u32 s16, s16, 0x40000
	s_addc_u32 s17, s17, 0
	v_exp_f32_e32 v12, v12
	v_exp_f32_e32 v13, v13
	s_waitcnt vmcnt(63)
	v_lshlrev_b32_e32 v16, 16, v34
	v_and_b32_e32 v17, 0xffff0000, v34
	v_pk_mul_f32 v[14:15], v[10:11], v[12:13]
	v_pk_fma_f32 v[10:11], v[10:11], v[12:13], v[16:17]
	v_cvt_pk_bf16_f32 v19, v14, v15
	v_mul_f32_e32 v12, 0x3fb8aa3b, v148
	v_mul_f32_e32 v13, 0x3fb8aa3b, v149
	global_store_dword v2, v19, s[16:17]
	s_add_u32 s16, s16, 0x40000
	s_addc_u32 s17, s17, 0
	v_exp_f32_e32 v12, v12
	v_exp_f32_e32 v13, v13
	s_waitcnt vmcnt(63)
	v_lshlrev_b32_e32 v16, 16, v35
	v_and_b32_e32 v17, 0xffff0000, v35
	v_pk_mul_f32 v[14:15], v[10:11], v[12:13]
	v_pk_fma_f32 v[10:11], v[10:11], v[12:13], v[16:17]
	v_cvt_pk_bf16_f32 v22, v14, v15
	v_mul_f32_e32 v12, 0x3fb8aa3b, v150
	v_mul_f32_e32 v13, 0x3fb8aa3b, v151
	global_store_dword v2, v22, s[16:17]
	s_add_u32 s16, s16, 0x40000
	s_addc_u32 s17, s17, 0
	v_exp_f32_e32 v12, v12
	v_exp_f32_e32 v13, v13
	s_waitcnt vmcnt(63)
	v_lshlrev_b32_e32 v16, 16, v36
	v_and_b32_e32 v17, 0xffff0000, v36
	v_pk_mul_f32 v[14:15], v[10:11], v[12:13]
	v_pk_fma_f32 v[10:11], v[10:11], v[12:13], v[16:17]
	v_cvt_pk_bf16_f32 v18, v14, v15
	v_mul_f32_e32 v12, 0x3fb8aa3b, v152
	v_mul_f32_e32 v13, 0x3fb8aa3b, v153
	global_store_dword v2, v18, s[16:17]
	s_add_u32 s16, s16, 0x40000
	s_addc_u32 s17, s17, 0
	v_exp_f32_e32 v12, v12
	v_exp_f32_e32 v13, v13
	s_waitcnt vmcnt(63)
	v_lshlrev_b32_e32 v16, 16, v37
	v_and_b32_e32 v17, 0xffff0000, v37
	v_pk_mul_f32 v[14:15], v[10:11], v[12:13]
	v_pk_fma_f32 v[10:11], v[10:11], v[12:13], v[16:17]
	v_cvt_pk_bf16_f32 v19, v14, v15
	v_mul_f32_e32 v12, 0x3fb8aa3b, v154
	v_mul_f32_e32 v13, 0x3fb8aa3b, v155
	global_store_dword v2, v19, s[16:17]
	s_add_u32 s16, s16, 0x40000
	s_addc_u32 s17, s17, 0
	v_exp_f32_e32 v12, v12
	v_exp_f32_e32 v13, v13
	s_waitcnt vmcnt(63)
	v_lshlrev_b32_e32 v16, 16, v38
	v_and_b32_e32 v17, 0xffff0000, v38
	v_pk_mul_f32 v[14:15], v[10:11], v[12:13]
	v_pk_fma_f32 v[10:11], v[10:11], v[12:13], v[16:17]
	v_cvt_pk_bf16_f32 v22, v14, v15
	v_mul_f32_e32 v12, 0x3fb8aa3b, v170
	v_mul_f32_e32 v13, 0x3fb8aa3b, v171
	global_store_dword v2, v22, s[16:17]
	s_add_u32 s16, s16, 0x40000
	s_addc_u32 s17, s17, 0
	v_exp_f32_e32 v12, v12
	v_exp_f32_e32 v13, v13
	s_waitcnt vmcnt(63)
	v_lshlrev_b32_e32 v16, 16, v39
	v_and_b32_e32 v17, 0xffff0000, v39
	v_pk_mul_f32 v[14:15], v[10:11], v[12:13]
	v_pk_fma_f32 v[10:11], v[10:11], v[12:13], v[16:17]
	v_cvt_pk_bf16_f32 v18, v14, v15
	v_mul_f32_e32 v12, 0x3fb8aa3b, v172
	v_mul_f32_e32 v13, 0x3fb8aa3b, v173
	global_store_dword v2, v18, s[16:17]
	s_add_u32 s16, s16, 0x40000
	s_addc_u32 s17, s17, 0
	v_exp_f32_e32 v12, v12
	v_exp_f32_e32 v13, v13
	s_waitcnt vmcnt(63)
	v_lshlrev_b32_e32 v16, 16, v40
	v_and_b32_e32 v17, 0xffff0000, v40
	v_pk_mul_f32 v[14:15], v[10:11], v[12:13]
	v_pk_fma_f32 v[10:11], v[10:11], v[12:13], v[16:17]
	v_cvt_pk_bf16_f32 v19, v14, v15
	v_mul_f32_e32 v12, 0x3fb8aa3b, v174
	v_mul_f32_e32 v13, 0x3fb8aa3b, v175
	global_store_dword v2, v19, s[16:17]
	s_add_u32 s16, s16, 0x40000
	s_addc_u32 s17, s17, 0
	v_exp_f32_e32 v12, v12
	v_exp_f32_e32 v13, v13
	s_waitcnt vmcnt(63)
	v_lshlrev_b32_e32 v16, 16, v41
	v_and_b32_e32 v17, 0xffff0000, v41
	v_pk_mul_f32 v[14:15], v[10:11], v[12:13]
	v_pk_fma_f32 v[10:11], v[10:11], v[12:13], v[16:17]
	v_cvt_pk_bf16_f32 v22, v14, v15
	v_mul_f32_e32 v12, 0x3fb8aa3b, v176
	v_mul_f32_e32 v13, 0x3fb8aa3b, v177
	global_store_dword v2, v22, s[16:17]
	s_add_u32 s16, s16, 0x40000
	s_addc_u32 s17, s17, 0
	v_exp_f32_e32 v12, v12
	v_exp_f32_e32 v13, v13
	s_waitcnt vmcnt(63)
	v_lshlrev_b32_e32 v16, 16, v42
	v_and_b32_e32 v17, 0xffff0000, v42
	v_pk_mul_f32 v[14:15], v[10:11], v[12:13]
	v_pk_fma_f32 v[10:11], v[10:11], v[12:13], v[16:17]
	v_cvt_pk_bf16_f32 v18, v14, v15
	v_mul_f32_e32 v12, 0x3fb8aa3b, v178
	v_mul_f32_e32 v13, 0x3fb8aa3b, v179
	global_store_dword v2, v18, s[16:17]
	s_add_u32 s16, s16, 0x40000
	s_addc_u32 s17, s17, 0
	v_exp_f32_e32 v12, v12
	v_exp_f32_e32 v13, v13
	s_waitcnt vmcnt(61)
	v_lshlrev_b32_e32 v16, 16, v43
	v_and_b32_e32 v17, 0xffff0000, v43
	v_pk_mul_f32 v[14:15], v[10:11], v[12:13]
	v_pk_fma_f32 v[10:11], v[10:11], v[12:13], v[16:17]
	v_cvt_pk_bf16_f32 v19, v14, v15
	v_mul_f32_e32 v12, 0x3fb8aa3b, v180
	v_mul_f32_e32 v13, 0x3fb8aa3b, v181
	global_store_dword v2, v19, s[16:17]
	s_add_u32 s16, s16, 0x40000
	s_addc_u32 s17, s17, 0
	v_exp_f32_e32 v12, v12
	v_exp_f32_e32 v13, v13
	s_waitcnt vmcnt(59)
	v_lshlrev_b32_e32 v16, 16, v44
	v_and_b32_e32 v17, 0xffff0000, v44
	v_pk_mul_f32 v[14:15], v[10:11], v[12:13]
	v_pk_fma_f32 v[10:11], v[10:11], v[12:13], v[16:17]
	v_cvt_pk_bf16_f32 v22, v14, v15
	v_mul_f32_e32 v12, 0x3fb8aa3b, v182
	v_mul_f32_e32 v13, 0x3fb8aa3b, v183
	global_store_dword v2, v22, s[16:17]
	s_add_u32 s16, s16, 0x40000
	s_addc_u32 s17, s17, 0
	v_exp_f32_e32 v12, v12
	v_exp_f32_e32 v13, v13
	s_waitcnt vmcnt(57)
	v_lshlrev_b32_e32 v16, 16, v45
	v_and_b32_e32 v17, 0xffff0000, v45
	v_pk_mul_f32 v[14:15], v[10:11], v[12:13]
	v_pk_fma_f32 v[10:11], v[10:11], v[12:13], v[16:17]
	v_cvt_pk_bf16_f32 v18, v14, v15
	v_mul_f32_e32 v12, 0x3fb8aa3b, v188
	v_mul_f32_e32 v13, 0x3fb8aa3b, v189
	global_store_dword v2, v18, s[16:17]
	s_add_u32 s16, s16, 0x40000
	s_addc_u32 s17, s17, 0
	v_exp_f32_e32 v12, v12
	v_exp_f32_e32 v13, v13
	s_waitcnt vmcnt(55)
	v_lshlrev_b32_e32 v16, 16, v46
	v_and_b32_e32 v17, 0xffff0000, v46
	v_pk_mul_f32 v[14:15], v[10:11], v[12:13]
	v_pk_fma_f32 v[10:11], v[10:11], v[12:13], v[16:17]
	v_cvt_pk_bf16_f32 v19, v14, v15
	v_mul_f32_e32 v12, 0x3fb8aa3b, v190
	v_mul_f32_e32 v13, 0x3fb8aa3b, v191
	global_store_dword v2, v19, s[16:17]
	s_add_u32 s16, s16, 0x40000
	s_addc_u32 s17, s17, 0
	v_exp_f32_e32 v12, v12
	v_exp_f32_e32 v13, v13
	s_waitcnt vmcnt(53)
	v_lshlrev_b32_e32 v16, 16, v50
	v_and_b32_e32 v17, 0xffff0000, v50
	v_pk_mul_f32 v[14:15], v[10:11], v[12:13]
	v_pk_fma_f32 v[10:11], v[10:11], v[12:13], v[16:17]
	v_cvt_pk_bf16_f32 v22, v14, v15
	v_mul_f32_e32 v12, 0x3fb8aa3b, v192
	v_mul_f32_e32 v13, 0x3fb8aa3b, v193
	global_store_dword v2, v22, s[16:17]
	s_add_u32 s16, s16, 0x40000
	s_addc_u32 s17, s17, 0
	v_exp_f32_e32 v12, v12
	v_exp_f32_e32 v13, v13
	s_waitcnt vmcnt(51)
	v_lshlrev_b32_e32 v16, 16, v51
	v_and_b32_e32 v17, 0xffff0000, v51
	v_pk_mul_f32 v[14:15], v[10:11], v[12:13]
	v_pk_fma_f32 v[10:11], v[10:11], v[12:13], v[16:17]
	v_cvt_pk_bf16_f32 v18, v14, v15
	v_mul_f32_e32 v12, 0x3fb8aa3b, v194
	v_mul_f32_e32 v13, 0x3fb8aa3b, v195
	global_store_dword v2, v18, s[16:17]
	s_add_u32 s16, s16, 0x40000
	s_addc_u32 s17, s17, 0
	v_exp_f32_e32 v12, v12
	v_exp_f32_e32 v13, v13
	s_waitcnt vmcnt(49)
	v_lshlrev_b32_e32 v16, 16, v52
	v_and_b32_e32 v17, 0xffff0000, v52
	v_pk_mul_f32 v[14:15], v[10:11], v[12:13]
	v_pk_fma_f32 v[10:11], v[10:11], v[12:13], v[16:17]
	v_cvt_pk_bf16_f32 v19, v14, v15
	v_mul_f32_e32 v12, 0x3fb8aa3b, v196
	v_mul_f32_e32 v13, 0x3fb8aa3b, v197
	global_store_dword v2, v19, s[16:17]
	s_add_u32 s16, s16, 0x40000
	s_addc_u32 s17, s17, 0
	v_exp_f32_e32 v12, v12
	v_exp_f32_e32 v13, v13
	s_waitcnt vmcnt(47)
	v_lshlrev_b32_e32 v16, 16, v53
	v_and_b32_e32 v17, 0xffff0000, v53
	v_pk_mul_f32 v[14:15], v[10:11], v[12:13]
	v_pk_fma_f32 v[10:11], v[10:11], v[12:13], v[16:17]
	v_cvt_pk_bf16_f32 v22, v14, v15
	v_mul_f32_e32 v12, 0x3fb8aa3b, v198
	v_mul_f32_e32 v13, 0x3fb8aa3b, v199
	global_store_dword v2, v22, s[16:17]
	s_add_u32 s16, s16, 0x40000
	s_addc_u32 s17, s17, 0
	v_exp_f32_e32 v12, v12
	v_exp_f32_e32 v13, v13
	s_waitcnt vmcnt(45)
	v_lshlrev_b32_e32 v16, 16, v54
	v_and_b32_e32 v17, 0xffff0000, v54
	v_pk_mul_f32 v[14:15], v[10:11], v[12:13]
	v_pk_fma_f32 v[10:11], v[10:11], v[12:13], v[16:17]
	v_cvt_pk_bf16_f32 v18, v14, v15
	v_mul_f32_e32 v12, 0x3fb8aa3b, v202
	v_mul_f32_e32 v13, 0x3fb8aa3b, v203
	global_store_dword v2, v18, s[16:17]
	s_add_u32 s16, s16, 0x40000
	s_addc_u32 s17, s17, 0
	v_exp_f32_e32 v12, v12
	v_exp_f32_e32 v13, v13
	s_waitcnt vmcnt(43)
	v_lshlrev_b32_e32 v16, 16, v55
	v_and_b32_e32 v17, 0xffff0000, v55
	v_pk_mul_f32 v[14:15], v[10:11], v[12:13]
	v_pk_fma_f32 v[10:11], v[10:11], v[12:13], v[16:17]
	v_cvt_pk_bf16_f32 v19, v14, v15
	v_mul_f32_e32 v12, 0x3fb8aa3b, v204
	v_mul_f32_e32 v13, 0x3fb8aa3b, v205
	global_store_dword v2, v19, s[16:17]
	s_add_u32 s16, s16, 0x40000
	s_addc_u32 s17, s17, 0
	v_exp_f32_e32 v12, v12
	v_exp_f32_e32 v13, v13
	s_waitcnt vmcnt(41)
	v_lshlrev_b32_e32 v16, 16, v56
	v_and_b32_e32 v17, 0xffff0000, v56
	v_pk_mul_f32 v[14:15], v[10:11], v[12:13]
	v_pk_fma_f32 v[10:11], v[10:11], v[12:13], v[16:17]
	v_cvt_pk_bf16_f32 v22, v14, v15
	v_mul_f32_e32 v12, 0x3fb8aa3b, v206
	v_mul_f32_e32 v13, 0x3fb8aa3b, v207
	global_store_dword v2, v22, s[16:17]
	s_add_u32 s16, s16, 0x40000
	s_addc_u32 s17, s17, 0
	v_exp_f32_e32 v12, v12
	v_exp_f32_e32 v13, v13
	s_waitcnt vmcnt(39)
	v_lshlrev_b32_e32 v16, 16, v57
	v_and_b32_e32 v17, 0xffff0000, v57
	v_pk_mul_f32 v[14:15], v[10:11], v[12:13]
	v_pk_fma_f32 v[10:11], v[10:11], v[12:13], v[16:17]
	v_cvt_pk_bf16_f32 v18, v14, v15
	v_mul_f32_e32 v12, 0x3fb8aa3b, v208
	v_mul_f32_e32 v13, 0x3fb8aa3b, v209
	global_store_dword v2, v18, s[16:17]
	s_add_u32 s16, s16, 0x40000
	s_addc_u32 s17, s17, 0
	v_exp_f32_e32 v12, v12
	v_exp_f32_e32 v13, v13
	s_waitcnt vmcnt(37)
	v_lshlrev_b32_e32 v16, 16, v58
	v_and_b32_e32 v17, 0xffff0000, v58
	v_pk_mul_f32 v[14:15], v[10:11], v[12:13]
	v_pk_fma_f32 v[10:11], v[10:11], v[12:13], v[16:17]
	v_cvt_pk_bf16_f32 v19, v14, v15
	v_mul_f32_e32 v12, 0x3fb8aa3b, v210
	v_mul_f32_e32 v13, 0x3fb8aa3b, v211
	global_store_dword v2, v19, s[16:17]
	s_add_u32 s16, s16, 0x40000
	s_addc_u32 s17, s17, 0
	v_exp_f32_e32 v12, v12
	v_exp_f32_e32 v13, v13
	s_waitcnt vmcnt(35)
	v_lshlrev_b32_e32 v16, 16, v59
	v_and_b32_e32 v17, 0xffff0000, v59
	v_pk_mul_f32 v[14:15], v[10:11], v[12:13]
	v_pk_fma_f32 v[10:11], v[10:11], v[12:13], v[16:17]
	v_cvt_pk_bf16_f32 v22, v14, v15
	v_mul_f32_e32 v12, 0x3fb8aa3b, v212
	v_mul_f32_e32 v13, 0x3fb8aa3b, v213
	global_store_dword v2, v22, s[16:17]
	s_add_u32 s16, s16, 0x40000
	s_addc_u32 s17, s17, 0
	v_exp_f32_e32 v12, v12
	v_exp_f32_e32 v13, v13
	s_waitcnt vmcnt(33)
	v_lshlrev_b32_e32 v16, 16, v60
	v_and_b32_e32 v17, 0xffff0000, v60
	v_pk_mul_f32 v[14:15], v[10:11], v[12:13]
	v_pk_fma_f32 v[10:11], v[10:11], v[12:13], v[16:17]
	v_cvt_pk_bf16_f32 v18, v14, v15
	v_mul_f32_e32 v12, 0x3fb8aa3b, v214
	v_mul_f32_e32 v13, 0x3fb8aa3b, v215
	global_store_dword v2, v18, s[16:17]
	s_add_u32 s16, s16, 0x40000
	s_addc_u32 s17, s17, 0
	v_exp_f32_e32 v12, v12
	v_exp_f32_e32 v13, v13
	s_waitcnt vmcnt(31)
	v_lshlrev_b32_e32 v16, 16, v61
	v_and_b32_e32 v17, 0xffff0000, v61
	v_pk_mul_f32 v[14:15], v[10:11], v[12:13]
	v_pk_fma_f32 v[10:11], v[10:11], v[12:13], v[16:17]
	v_cvt_pk_bf16_f32 v19, v14, v15
	v_mul_f32_e32 v12, 0x3fb8aa3b, v216
	v_mul_f32_e32 v13, 0x3fb8aa3b, v217
	global_store_dword v2, v19, s[16:17]
	s_add_u32 s16, s16, 0x40000
	s_addc_u32 s17, s17, 0
	v_exp_f32_e32 v12, v12
	v_exp_f32_e32 v13, v13
	v_add_u32_e32 v20, s0, v20
	s_mov_b32 s9, 0xffff
	v_cmp_lt_i32_e32 vcc, s9, v20
	s_or_b64 s[10:11], vcc, s[10:11]
	v_add_u32_e32 v21, s3, v21
	s_andn2_b64 exec, exec, s[10:11]
	s_cbranch_execnz .LBB0_1056

.LBB0_1212:
	v_readlane_b32 s4, v255, 15
	v_readlane_b32 s5, v255, 16
	s_andn2_b64 vcc, exec, s[4:5]
	s_cbranch_vccnz .LBB0_2210
	v_readfirstlane_b32 s0, v0
	s_bfe_u32 s100, s0, 0x10008
	v_mov_b32_e32 v2, v0
	v_readlane_b32 s0, v254, 4
	s_nop 0
	v_readlane_b32 s0, v254, 2
	s_mov_b32 s27, s0
	v_readlane_b32 s0, v254, 3
	s_mov_b32 s30, s0
	s_cmpk_gt_i32 s30, 0xff
	s_cbranch_scc1 .LBB0_1540
	s_mov_b32 s0, s30
	v_writelane_b32 v255, s27, 53
	s_branch .LBB0_1216

.LBB0_1227:
	s_cmp_eq_u32 s100, 0
	s_cbranch_scc1 .Lblkb2_a
	s_barrier
	v_max_f32_e32 v148, v83, v83
	v_max_f32_e32 v149, v82, v82
	v_max_f32_e32 v148, v149, v148
	v_max3_f32 v148, v148, v84, v85
	v_max3_f32 v148, v148, v86, v87
	v_max3_f32 v148, v148, v88, v89
	v_max3_f32 v148, v148, v90, v91
	v_max3_f32 v148, v148, v92, v93
	v_max3_f32 v148, v148, v94, v95
	v_max3_f32 v148, v148, v96, v97
	v_max3_f32 v148, v148, v66, v67
	v_max3_f32 v148, v148, v68, v69
	v_max3_f32 v148, v148, v70, v71
	v_max3_f32 v148, v148, v72, v73
	v_max3_f32 v148, v148, v74, v75
	v_max3_f32 v148, v148, v76, v77
	v_max3_f32 v148, v148, v78, v79
	v_max3_f32 v148, v148, v80, v81
	v_mov_b32_e32 v149, v148
	s_nop 1
	v_permlane32_swap_b32_e32 v148, v149
	v_max_f32_e32 v149, v149, v149
	v_max_f32_e32 v148, v148, v148
	v_max_f32_e32 v148, v148, v149
	v_sub_f32_e32 v149, v148, v156
	v_mul_f32_e32 v149, 0x3db504f3, v149
	v_cmp_ge_f32_e32 vcc, s2, v149
	v_max_f32_e32 v149, v156, v156
	v_max_f32_e32 v148, v149, v148
	v_sub_f32_e32 v149, v156, v148
	v_mul_f32_e32 v149, 0x3e0293ee, v149
	v_exp_f32_e32 v149, v149
	s_cmp_eq_u64 vcc, exec
	s_cselect_b64 s[40:41], -1, 0
	s_branch .Lblkb2_j

.Lblkb2_j:
	s_waitcnt vmcnt(0)
	v_cndmask_b32_e64 v199, v149, 1.0, s[40:41]
	v_cmp_gt_f32_e32 vcc, 1.0, v199
	s_waitcnt vmcnt(3)
	ds_write_b128 v190, v[132:135]
	s_waitcnt vmcnt(2)
	ds_write_b128 v191, v[136:139]
	s_waitcnt vmcnt(1)
	ds_write_b128 v180, v[140:143] offset:32768
	s_waitcnt vmcnt(0)
	ds_write_b128 v181, v[144:147] offset:32768
	s_cbranch_vccz .LBB0_1231
	s_and_saveexec_b64 s[4:5], s[38:39]
	ds_write_b32 v186, v199 offset:128
	s_or_b64 exec, exec, s[4:5]
	s_waitcnt lgkmcnt(0)
	ds_read_b128 v[150:153], v185 offset:224
	ds_read_b128 v[158:161], v185 offset:192
	ds_read_b128 v[202:205], v185 offset:160
	ds_read_b128 v[206:209], v185 offset:128
	s_waitcnt lgkmcnt(3)
	v_pk_mul_f32 v[48:49], v[48:49], v[152:153]
	s_waitcnt lgkmcnt(2)
	v_pk_mul_f32 v[44:45], v[44:45], v[160:161]
	s_waitcnt lgkmcnt(1)
	v_pk_mul_f32 v[40:41], v[40:41], v[204:205]
	s_waitcnt lgkmcnt(0)
	v_pk_mul_f32 v[36:37], v[36:37], v[208:209]
	v_pk_mul_f32 v[46:47], v[46:47], v[150:151]
	v_pk_mul_f32 v[42:43], v[42:43], v[158:159]
	v_pk_mul_f32 v[38:39], v[38:39], v[202:203]
	v_pk_mul_f32 v[34:35], v[34:35], v[206:207]
	v_pk_mul_f32 v[64:65], v[64:65], v[152:153]
	v_pk_mul_f32 v[60:61], v[60:61], v[160:161]
	v_pk_mul_f32 v[56:57], v[56:57], v[204:205]
	v_pk_mul_f32 v[52:53], v[52:53], v[208:209]
	v_pk_mul_f32 v[62:63], v[62:63], v[150:151]
	v_pk_mul_f32 v[58:59], v[58:59], v[158:159]
	v_pk_mul_f32 v[54:55], v[54:55], v[202:203]
	v_pk_mul_f32 v[50:51], v[50:51], v[206:207]
	v_pk_mul_f32 v[32:33], v[32:33], v[152:153]
	v_pk_mul_f32 v[28:29], v[28:29], v[160:161]
	v_pk_mul_f32 v[24:25], v[24:25], v[204:205]
	v_pk_mul_f32 v[20:21], v[20:21], v[208:209]
	v_pk_mul_f32 v[30:31], v[30:31], v[150:151]
	v_pk_mul_f32 v[26:27], v[26:27], v[158:159]
	v_pk_mul_f32 v[22:23], v[22:23], v[202:203]
	v_pk_mul_f32 v[18:19], v[18:19], v[206:207]
	v_pk_mul_f32 v[16:17], v[16:17], v[152:153]
	v_pk_mul_f32 v[12:13], v[12:13], v[160:161]
	v_pk_mul_f32 v[8:9], v[8:9], v[204:205]
	v_pk_mul_f32 v[4:5], v[4:5], v[208:209]
	v_pk_mul_f32 v[14:15], v[14:15], v[150:151]
	v_pk_mul_f32 v[10:11], v[10:11], v[158:159]
	v_pk_mul_f32 v[6:7], v[6:7], v[202:203]
	v_pk_mul_f32 v[2:3], v[2:3], v[206:207]
.LBB0_1231:
	s_cmp_eq_u32 s100, 0
	s_cbranch_scc1 .Lblk2_a
	s_waitcnt lgkmcnt(0)
	s_barrier
	v_cndmask_b32_e64 v201, v148, v156, s[40:41]
	v_mul_f32_e32 v206, 0xbe0293ee, v201
	v_fmamk_f32 v82, v82, 0x3e0293ee, v206
	v_fmamk_f32 v83, v83, 0x3e0293ee, v206
	v_fmamk_f32 v84, v84, 0x3e0293ee, v206
	v_fmamk_f32 v85, v85, 0x3e0293ee, v206
	v_fmamk_f32 v86, v86, 0x3e0293ee, v206
	v_fmamk_f32 v87, v87, 0x3e0293ee, v206
	v_fmamk_f32 v88, v88, 0x3e0293ee, v206
	v_fmamk_f32 v89, v89, 0x3e0293ee, v206
	v_fmamk_f32 v90, v90, 0x3e0293ee, v206
	v_fmamk_f32 v91, v91, 0x3e0293ee, v206
	v_fmamk_f32 v92, v92, 0x3e0293ee, v206
	v_fmamk_f32 v93, v93, 0x3e0293ee, v206
	v_fmamk_f32 v94, v94, 0x3e0293ee, v206
	v_fmamk_f32 v95, v95, 0x3e0293ee, v206
	v_fmamk_f32 v96, v96, 0x3e0293ee, v206
	v_fmamk_f32 v97, v97, 0x3e0293ee, v206
	v_exp_f32_e32 v148, v82
	v_exp_f32_e32 v163, v83
	v_exp_f32_e32 v149, v84
	v_exp_f32_e32 v162, v85
	v_exp_f32_e32 v150, v86
	v_exp_f32_e32 v161, v87
	v_exp_f32_e32 v151, v88
	v_exp_f32_e32 v160, v89
	v_exp_f32_e32 v152, v90
	v_exp_f32_e32 v159, v91
	v_exp_f32_e32 v153, v92
	v_exp_f32_e32 v158, v93
	v_exp_f32_e32 v154, v94
	v_exp_f32_e32 v157, v95
	v_exp_f32_e32 v155, v96
	v_exp_f32_e32 v156, v97
	v_fmamk_f32 v215, v66, 0x3e0293ee, v206
	v_fmamk_f32 v216, v67, 0x3e0293ee, v206
	v_fmamk_f32 v217, v68, 0x3e0293ee, v206
	v_fmamk_f32 v218, v69, 0x3e0293ee, v206
	v_fmamk_f32 v219, v70, 0x3e0293ee, v206
	v_fmamk_f32 v208, v71, 0x3e0293ee, v206
	v_fmamk_f32 v209, v72, 0x3e0293ee, v206
	v_fmamk_f32 v210, v73, 0x3e0293ee, v206
	v_fmamk_f32 v211, v74, 0x3e0293ee, v206
	v_fmamk_f32 v212, v75, 0x3e0293ee, v206
	v_fmamk_f32 v213, v76, 0x3e0293ee, v206
	v_fmamk_f32 v214, v77, 0x3e0293ee, v206
	v_fmamk_f32 v207, v78, 0x3e0293ee, v206
	v_fmamk_f32 v220, v79, 0x3e0293ee, v206
	v_fmamk_f32 v221, v80, 0x3e0293ee, v206
	v_fmac_f32_e32 v206, 0x3e0293ee, v81
	s_branch .Lblk2_j

.Lblk2_j:
	ds_read_b128 v[82:85], v195 offset:256
	ds_read_b128 v[86:89], v195 offset:288
	ds_read_b128 v[66:69], v195 offset:384
	ds_read_b128 v[70:73], v195 offset:416
	ds_read_b128 v[90:93], v195 offset:320
	ds_read_b128 v[74:77], v195 offset:448
	ds_read_b128 v[94:97], v195 offset:352
	ds_read_b128 v[78:81], v195 offset:480
	ds_read_b128 v[202:205], v189 offset:32768
	ds_read_b128 v[222:225], v189 offset:33280
	v_exp_f32_e32 v208, v208
	v_exp_f32_e32 v209, v209
	v_exp_f32_e32 v210, v210
	s_waitcnt lgkmcnt(1)
	v_mfma_f32_32x32x16_bf16 v[82:97], v[202:205], v[128:131], v[82:97]
	v_exp_f32_e32 v211, v211
	v_exp_f32_e32 v212, v212
	v_exp_f32_e32 v213, v213
	v_exp_f32_e32 v214, v214
	s_waitcnt lgkmcnt(0)
	v_mfma_f32_32x32x16_bf16 v[66:81], v[222:225], v[128:131], v[66:81]
	ds_read_b128 v[202:205], v189 offset:35104
	ds_read_b128 v[222:225], v189 offset:35616
	s_waitcnt lgkmcnt(1)
	v_mfma_f32_32x32x16_bf16 v[82:97], v[202:205], v[124:127], v[82:97]
	s_waitcnt lgkmcnt(0)
	v_mfma_f32_32x32x16_bf16 v[66:81], v[222:225], v[124:127], v[66:81]
	ds_read_b128 v[202:205], v189 offset:37440
	ds_read_b128 v[222:225], v189 offset:37952
	s_waitcnt lgkmcnt(1)
	v_mfma_f32_32x32x16_bf16 v[82:97], v[202:205], v[120:123], v[82:97]
	s_waitcnt lgkmcnt(0)
	v_mfma_f32_32x32x16_bf16 v[66:81], v[222:225], v[120:123], v[66:81]
	ds_read_b128 v[202:205], v189 offset:39776
	ds_read_b128 v[222:225], v189 offset:40288
	s_waitcnt lgkmcnt(1)
	v_mfma_f32_32x32x16_bf16 v[82:97], v[202:205], v[116:119], v[82:97]
	s_waitcnt lgkmcnt(0)
	v_mfma_f32_32x32x16_bf16 v[66:81], v[222:225], v[116:119], v[66:81]
	ds_read_b128 v[202:205], v189 offset:41984
	ds_read_b128 v[222:225], v189 offset:42496
	s_waitcnt lgkmcnt(1)
	v_mfma_f32_32x32x16_bf16 v[82:97], v[202:205], v[112:115], v[82:97]
	s_waitcnt lgkmcnt(0)
	v_mfma_f32_32x32x16_bf16 v[66:81], v[222:225], v[112:115], v[66:81]
	ds_read_b128 v[202:205], v189 offset:44320
	ds_read_b128 v[222:225], v189 offset:44832
	s_waitcnt lgkmcnt(1)
	v_mfma_f32_32x32x16_bf16 v[82:97], v[202:205], v[108:111], v[82:97]
	s_waitcnt lgkmcnt(0)
	v_mfma_f32_32x32x16_bf16 v[66:81], v[222:225], v[108:111], v[66:81]
	ds_read_b128 v[202:205], v189 offset:46656
	ds_read_b128 v[222:225], v189 offset:47168
	s_waitcnt lgkmcnt(1)
	v_mfma_f32_32x32x16_bf16 v[82:97], v[202:205], v[104:107], v[82:97]
	s_waitcnt lgkmcnt(0)
	v_mfma_f32_32x32x16_bf16 v[66:81], v[222:225], v[104:107], v[66:81]
	ds_read_b128 v[202:205], v189 offset:48992
	ds_read_b128 v[222:225], v189 offset:49504
	s_waitcnt lgkmcnt(1)
	v_mfma_f32_32x32x16_bf16 v[82:97], v[202:205], v[100:103], v[82:97]
	v_exp_f32_e32 v202, v215
	v_exp_f32_e32 v215, v219
	v_exp_f32_e32 v219, v206
	v_add_f32_e32 v206, 0, v148
	v_add_f32_e32 v206, v163, v206
	v_add_f32_e32 v206, v149, v206
	v_add_f32_e32 v206, v162, v206
	v_add_f32_e32 v206, v150, v206
	v_add_f32_e32 v206, v161, v206
	v_add_f32_e32 v206, v151, v206
	v_add_f32_e32 v206, v160, v206
	v_add_f32_e32 v206, v152, v206
	v_add_f32_e32 v206, v159, v206
	v_add_f32_e32 v206, v153, v206
	v_add_f32_e32 v206, v158, v206
	v_add_f32_e32 v206, v154, v206
	v_exp_f32_e32 v203, v216
	v_add_f32_e32 v206, v157, v206
	v_exp_f32_e32 v204, v217
	v_add_f32_e32 v206, v155, v206
	v_exp_f32_e32 v205, v218
	v_add_f32_e32 v206, v156, v206
	v_add_f32_e32 v206, v202, v206
	v_add_f32_e32 v206, v203, v206
	v_add_f32_e32 v206, v204, v206
	v_add_f32_e32 v206, v205, v206
	v_add_f32_e32 v206, v215, v206
	v_add_f32_e32 v206, v208, v206
	v_add_f32_e32 v206, v209, v206
	v_add_f32_e32 v206, v210, v206
	v_exp_f32_e32 v216, v207
	v_add_f32_e32 v206, v211, v206
	v_exp_f32_e32 v217, v220
	v_add_f32_e32 v206, v212, v206
	s_waitcnt lgkmcnt(0)
	v_mfma_f32_32x32x16_bf16 v[66:81], v[222:225], v[100:103], v[66:81]
	v_exp_f32_e32 v218, v221
	v_add_f32_e32 v206, v213, v206
	v_add_f32_e32 v206, v214, v206
	v_add_f32_e32 v206, v216, v206
	v_add_f32_e32 v206, v217, v206
	v_add_f32_e32 v206, v218, v206
	v_add_f32_e32 v206, v219, v206
	v_mov_b32_e32 v207, v206
	v_cvt_pk_bf16_f32 v148, v148, v163
	v_cvt_pk_bf16_f32 v149, v149, v162
	v_cvt_pk_bf16_f32 v150, v150, v161
	v_cvt_pk_bf16_f32 v151, v151, v160
	v_cvt_pk_bf16_f32 v152, v152, v159
	v_cvt_pk_bf16_f32 v153, v153, v158
	v_cvt_pk_bf16_f32 v154, v154, v157
	v_cvt_pk_bf16_f32 v155, v155, v156
	v_cvt_pk_bf16_f32 v156, v202, v203
	v_cvt_pk_bf16_f32 v157, v204, v205
	v_cvt_pk_bf16_f32 v158, v215, v208
	v_cvt_pk_bf16_f32 v159, v209, v210
	v_cvt_pk_bf16_f32 v160, v211, v212
	v_cvt_pk_bf16_f32 v161, v213, v214
	v_cvt_pk_bf16_f32 v162, v216, v217
	v_cvt_pk_bf16_f32 v163, v218, v219
	s_nop 1
	v_permlane32_swap_b32_e32 v206, v207
	v_permlane32_swap_b32_e32 v148, v150
	v_permlane32_swap_b32_e32 v149, v151
	v_permlane32_swap_b32_e32 v152, v154
	v_permlane32_swap_b32_e32 v153, v155
	v_permlane32_swap_b32_e32 v156, v158
	v_permlane32_swap_b32_e32 v157, v159
	v_permlane32_swap_b32_e32 v160, v162
	v_permlane32_swap_b32_e32 v161, v163
	s_add_i32 s4, s0, 1
	s_cmp_lt_u32 s4, s35
	s_cselect_b64 s[24:25], -1, 0
	s_cmp_ge_u32 s4, s35
	s_cbranch_scc1 .LBB0_1233
	v_add_co_u32_e32 v132, vcc, 0x241fb000, v178
	s_nop 1
	v_addc_co_u32_e32 v133, vcc, 0, v179, vcc
	v_add_co_u32_e32 v136, vcc, 0x242cf000, v178
	s_nop 1
	v_addc_co_u32_e32 v137, vcc, 0, v179, vcc
	v_add_co_u32_e32 v140, vcc, 0x4010c000, v176
	global_load_dwordx4 v[132:135], v[132:133], off
	s_nop 0
	global_load_dwordx4 v[136:139], v[136:137], off
	v_addc_co_u32_e32 v141, vcc, 0, v177, vcc
	v_add_co_u32_e32 v144, vcc, 0x4010e000, v176
	s_nop 1
	v_addc_co_u32_e32 v145, vcc, 0, v177, vcc
	global_load_dwordx4 v[140:143], v[140:141], off
	s_nop 0
	global_load_dwordx4 v[144:147], v[144:145], off

.LBB0_1235:
	s_cmp_eq_u32 s100, 0
	s_cbranch_scc1 .Lblkb3_a
	s_barrier
	v_max_f32_e32 v148, v83, v83
	v_max_f32_e32 v149, v82, v82
	v_max_f32_e32 v148, v149, v148
	v_max3_f32 v148, v148, v84, v85
	v_max3_f32 v148, v148, v86, v87
	v_max3_f32 v148, v148, v88, v89
	v_max3_f32 v148, v148, v90, v91
	v_max3_f32 v148, v148, v92, v93
	v_max3_f32 v148, v148, v94, v95
	v_max3_f32 v148, v148, v96, v97
	v_max3_f32 v148, v148, v66, v67
	v_max3_f32 v148, v148, v68, v69
	v_max3_f32 v148, v148, v70, v71
	v_max3_f32 v148, v148, v72, v73
	v_max3_f32 v148, v148, v74, v75
	v_max3_f32 v148, v148, v76, v77
	v_max3_f32 v148, v148, v78, v79
	v_max3_f32 v148, v148, v80, v81
	v_mov_b32_e32 v149, v148
	s_nop 1
	v_permlane32_swap_b32_e32 v148, v149
	v_max_f32_e32 v149, v149, v149
	v_max_f32_e32 v148, v148, v148
	v_max_f32_e32 v148, v148, v149
	v_sub_f32_e32 v149, v148, v201
	v_mul_f32_e32 v149, 0x3db504f3, v149
	v_cmp_ge_f32_e32 vcc, s2, v149
	s_cmp_eq_u64 vcc, exec
	s_cselect_b64 s[40:41], -1, 0
	s_andn2_b64 vcc, exec, s[24:25]
	s_branch .Lblkb3_j

.Lblkb3_j:
	s_cbranch_vccnz .LBB0_1237
	s_waitcnt vmcnt(0)
	s_waitcnt vmcnt(3)
	ds_write_b128 v190, v[132:135] offset:16384
	s_waitcnt vmcnt(2)
	ds_write_b128 v191, v[136:139] offset:16384
	s_waitcnt vmcnt(1)
	ds_write_b128 v180, v[140:143] offset:51200
	s_waitcnt vmcnt(0)
	ds_write_b128 v181, v[144:147] offset:51200

.LBB0_1241:
	s_cmp_eq_u32 s100, 0
	s_cbranch_scc1 .Lblk3_a
	s_waitcnt lgkmcnt(0)
	s_barrier
	v_cndmask_b32_e64 v156, v132, v201, s[40:41]
	v_mul_f32_e32 v134, 0xbe0293ee, v156
	v_mov_b32_e32 v135, v134
	v_fmamk_f32 v82, v82, 0x3e0293ee, v134
	v_fmamk_f32 v83, v83, 0x3e0293ee, v134
	v_fmamk_f32 v84, v84, 0x3e0293ee, v134
	v_fmamk_f32 v85, v85, 0x3e0293ee, v134
	v_fmamk_f32 v86, v86, 0x3e0293ee, v134
	v_fmamk_f32 v87, v87, 0x3e0293ee, v134
	v_fmamk_f32 v88, v88, 0x3e0293ee, v134
	v_fmamk_f32 v89, v89, 0x3e0293ee, v134
	v_fmamk_f32 v90, v90, 0x3e0293ee, v134
	v_fmamk_f32 v91, v91, 0x3e0293ee, v134
	v_fmamk_f32 v92, v92, 0x3e0293ee, v134
	v_fmamk_f32 v93, v93, 0x3e0293ee, v134
	v_fmamk_f32 v94, v94, 0x3e0293ee, v134
	v_fmamk_f32 v95, v95, 0x3e0293ee, v134
	v_fmamk_f32 v96, v96, 0x3e0293ee, v134
	v_fmac_f32_e32 v135, 0x3e0293ee, v97
	v_exp_f32_e32 v163, v82
	v_exp_f32_e32 v177, v83
	v_exp_f32_e32 v149, v84
	v_exp_f32_e32 v176, v85
	v_exp_f32_e32 v150, v86
	v_exp_f32_e32 v162, v87
	v_exp_f32_e32 v151, v88
	v_exp_f32_e32 v161, v89
	v_exp_f32_e32 v152, v90
	v_exp_f32_e32 v160, v91
	v_exp_f32_e32 v153, v92
	v_exp_f32_e32 v159, v93
	v_exp_f32_e32 v154, v94
	v_exp_f32_e32 v158, v95
	v_exp_f32_e32 v155, v96
	v_exp_f32_e32 v157, v135
	s_waitcnt vmcnt(0)
	v_pk_fma_f32 v[144:145], v[66:67], s[36:37], v[134:135] op_sel_hi:[1,0,0]
	v_add_f32_e32 v66, v197, v198
	s_mov_b64 s[4:5], 0x8000
	v_fmac_f32_e32 v66, v194, v187
	v_add_f32_e32 v187, v206, v207
	s_addk_i32 s11, 0x80
	v_lshl_add_u64 v[172:173], v[172:173], 0, s[4:5]
	s_add_i32 s0, s0, 2
	s_mov_b64 s[4:5], 0x350000
	v_pk_fma_f32 v[142:143], v[68:69], s[36:37], v[134:135] op_sel_hi:[1,0,0]
	v_pk_fma_f32 v[138:139], v[70:71], s[36:37], v[134:135] op_sel_hi:[1,0,0]
	v_pk_fma_f32 v[136:137], v[72:73], s[36:37], v[134:135] op_sel_hi:[1,0,0]
	v_pk_fma_f32 v[132:133], v[74:75], s[36:37], v[134:135] op_sel_hi:[1,0,0]
	v_pk_fma_f32 v[146:147], v[76:77], s[36:37], v[134:135] op_sel_hi:[1,0,0]
	v_pk_fma_f32 v[140:141], v[78:79], s[36:37], v[134:135] op_sel_hi:[1,0,0]
	v_pk_fma_f32 v[134:135], v[80:81], s[36:37], v[134:135] op_sel_hi:[1,0,0]
	v_fmac_f32_e32 v187, v66, v199
	v_add_u32_e32 v195, 0x200, v195
	v_add_u32_e32 v196, 0xffffff80, v196
	s_cmp_lt_u32 s0, s35
	v_lshl_add_u64 v[174:175], v[174:175], 0, s[4:5]
	s_branch .Lblk3_j

.Lblk3_j:
	s_cbranch_scc0 .LBB0_1243
	v_mov_b32_e32 v194, v148
	s_branch .LBB0_1225

.LBB0_1388:
	s_cmp_eq_u32 s100, 0
	s_cbranch_scc1 .Lblkb0_a
	s_barrier
	v_max_f32_e32 v168, v83, v83
	v_max_f32_e32 v169, v82, v82
	v_max_f32_e32 v168, v169, v168
	v_max3_f32 v168, v168, v84, v85
	v_max3_f32 v168, v168, v86, v87
	v_max3_f32 v168, v168, v88, v89
	v_max3_f32 v168, v168, v90, v91
	v_max3_f32 v168, v168, v92, v93
	v_max3_f32 v168, v168, v94, v95
	v_max3_f32 v168, v168, v96, v97
	v_max3_f32 v168, v168, v66, v67
	v_max3_f32 v168, v168, v68, v69
	v_max3_f32 v168, v168, v70, v71
	v_max3_f32 v168, v168, v72, v73
	v_max3_f32 v168, v168, v74, v75
	v_max3_f32 v168, v168, v76, v77
	v_max3_f32 v168, v168, v78, v79
	v_max3_f32 v168, v168, v80, v81
	v_mov_b32_e32 v169, v168
	s_nop 1
	v_permlane32_swap_b32_e32 v168, v169
	v_max_f32_e32 v169, v169, v169
	v_max_f32_e32 v168, v168, v168
	v_max_f32_e32 v168, v168, v169
	v_sub_f32_e32 v169, v168, v176
	v_mul_f32_e32 v169, 0x3d93cd3a, v169
	v_cmp_ge_f32_e32 vcc, s2, v169
	v_max_f32_e32 v169, v176, v176
	v_max_f32_e32 v168, v169, v168
	v_sub_f32_e32 v169, v176, v168
	v_mul_f32_e32 v169, 0x3dd53b94, v169
	v_exp_f32_e32 v169, v169
	s_cmp_eq_u64 vcc, exec
	s_cselect_b64 s[40:41], -1, 0
	s_branch .Lblkb0_j

.Lblkb0_j:
	s_waitcnt vmcnt(0)
	v_cndmask_b32_e64 v223, v169, 1.0, s[40:41]
	v_add_u32_e32 v206, 0x11000, v218
	v_cmp_gt_f32_e32 vcc, 1.0, v223
	s_waitcnt vmcnt(4)
	ds_write_b128 v212, v[148:151]
	s_waitcnt vmcnt(3)
	ds_write_b128 v213, v[152:155]
	s_waitcnt vmcnt(2)
	ds_write_b128 v196, v[156:159] offset:32768
	s_waitcnt vmcnt(1)
	ds_write_b128 v197, v[160:163] offset:32768
	s_waitcnt vmcnt(0)
	ds_write_b128 v206, v[164:167]
	s_cbranch_vccz .LBB0_1392
	s_and_saveexec_b64 s[4:5], s[38:39]
	ds_write_b32 v209, v223 offset:128
	s_or_b64 exec, exec, s[4:5]
	s_waitcnt lgkmcnt(0)
	ds_read_b128 v[170:173], v208 offset:224
	ds_read_b128 v[178:181], v208 offset:192
	ds_read_b128 v[228:231], v208 offset:160
	ds_read_b128 v[238:241], v208 offset:128
	s_waitcnt lgkmcnt(3)
	v_pk_mul_f32 v[48:49], v[48:49], v[172:173]
	s_waitcnt lgkmcnt(2)
	v_pk_mul_f32 v[44:45], v[44:45], v[180:181]
	s_waitcnt lgkmcnt(1)
	v_pk_mul_f32 v[40:41], v[40:41], v[230:231]
	s_waitcnt lgkmcnt(0)
	v_pk_mul_f32 v[36:37], v[36:37], v[240:241]
	v_pk_mul_f32 v[46:47], v[46:47], v[170:171]
	v_pk_mul_f32 v[42:43], v[42:43], v[178:179]
	v_pk_mul_f32 v[38:39], v[38:39], v[228:229]
	v_pk_mul_f32 v[34:35], v[34:35], v[238:239]
	v_pk_mul_f32 v[64:65], v[64:65], v[172:173]
	v_pk_mul_f32 v[60:61], v[60:61], v[180:181]
	v_pk_mul_f32 v[56:57], v[56:57], v[230:231]
	v_pk_mul_f32 v[52:53], v[52:53], v[240:241]
	v_pk_mul_f32 v[62:63], v[62:63], v[170:171]
	v_pk_mul_f32 v[58:59], v[58:59], v[178:179]
	v_pk_mul_f32 v[54:55], v[54:55], v[228:229]
	v_pk_mul_f32 v[50:51], v[50:51], v[238:239]
	v_pk_mul_f32 v[32:33], v[32:33], v[172:173]
	v_pk_mul_f32 v[28:29], v[28:29], v[180:181]
	v_pk_mul_f32 v[24:25], v[24:25], v[230:231]
	v_pk_mul_f32 v[20:21], v[20:21], v[240:241]
	v_pk_mul_f32 v[30:31], v[30:31], v[170:171]
	v_pk_mul_f32 v[26:27], v[26:27], v[178:179]
	v_pk_mul_f32 v[22:23], v[22:23], v[228:229]
	v_pk_mul_f32 v[18:19], v[18:19], v[238:239]
	v_pk_mul_f32 v[16:17], v[16:17], v[172:173]
	v_pk_mul_f32 v[12:13], v[12:13], v[180:181]
	v_pk_mul_f32 v[8:9], v[8:9], v[230:231]
	v_pk_mul_f32 v[4:5], v[4:5], v[240:241]
	v_pk_mul_f32 v[14:15], v[14:15], v[170:171]
	v_pk_mul_f32 v[10:11], v[10:11], v[178:179]
	v_pk_mul_f32 v[6:7], v[6:7], v[228:229]
	v_pk_mul_f32 v[2:3], v[2:3], v[238:239]
.LBB0_1392:
	s_cmp_eq_u32 s100, 0
	s_cbranch_scc1 .Lblk0_a
	s_waitcnt lgkmcnt(0)
	s_barrier
	v_cndmask_b32_e64 v224, v168, v176, s[40:41]
	v_mul_f32_e32 v227, 0xbdd53b94, v224
	v_fmamk_f32 v82, v82, 0x3dd53b94, v227
	v_fmamk_f32 v83, v83, 0x3dd53b94, v227
	v_fmamk_f32 v84, v84, 0x3dd53b94, v227
	v_fmamk_f32 v85, v85, 0x3dd53b94, v227
	v_fmamk_f32 v86, v86, 0x3dd53b94, v227
	v_fmamk_f32 v87, v87, 0x3dd53b94, v227
	v_fmamk_f32 v88, v88, 0x3dd53b94, v227
	v_fmamk_f32 v89, v89, 0x3dd53b94, v227
	v_fmamk_f32 v90, v90, 0x3dd53b94, v227
	v_fmamk_f32 v91, v91, 0x3dd53b94, v227
	v_fmamk_f32 v92, v92, 0x3dd53b94, v227
	v_fmamk_f32 v93, v93, 0x3dd53b94, v227
	v_fmamk_f32 v94, v94, 0x3dd53b94, v227
	v_fmamk_f32 v95, v95, 0x3dd53b94, v227
	v_fmamk_f32 v96, v96, 0x3dd53b94, v227
	v_fmamk_f32 v97, v97, 0x3dd53b94, v227
	v_exp_f32_e32 v168, v82
	v_exp_f32_e32 v183, v83
	v_exp_f32_e32 v169, v84
	v_exp_f32_e32 v182, v85
	v_exp_f32_e32 v170, v86
	v_exp_f32_e32 v181, v87
	v_exp_f32_e32 v171, v88
	v_exp_f32_e32 v180, v89
	v_exp_f32_e32 v172, v90
	v_exp_f32_e32 v179, v91
	v_exp_f32_e32 v173, v92
	v_exp_f32_e32 v178, v93
	v_exp_f32_e32 v174, v94
	v_exp_f32_e32 v177, v95
	v_exp_f32_e32 v175, v96
	v_exp_f32_e32 v176, v97
	v_fmamk_f32 v242, v66, 0x3dd53b94, v227
	v_fmamk_f32 v243, v67, 0x3dd53b94, v227
	v_fmamk_f32 v244, v68, 0x3dd53b94, v227
	v_fmamk_f32 v245, v69, 0x3dd53b94, v227
	v_fmamk_f32 v246, v70, 0x3dd53b94, v227
	v_fmamk_f32 v229, v71, 0x3dd53b94, v227
	v_fmamk_f32 v230, v72, 0x3dd53b94, v227
	v_fmamk_f32 v231, v73, 0x3dd53b94, v227
	v_fmamk_f32 v238, v74, 0x3dd53b94, v227
	v_fmamk_f32 v239, v75, 0x3dd53b94, v227
	v_fmamk_f32 v240, v76, 0x3dd53b94, v227
	v_fmamk_f32 v241, v77, 0x3dd53b94, v227
	v_fmamk_f32 v228, v78, 0x3dd53b94, v227
	v_fmamk_f32 v247, v79, 0x3dd53b94, v227
	v_fmamk_f32 v248, v80, 0x3dd53b94, v227
	v_fmac_f32_e32 v227, 0x3dd53b94, v81
	s_branch .Lblk0_j

.Lblk0_j:
	ds_read_b128 v[66:69], v211 offset:32768
	ds_read_b128 v[70:73], v211 offset:33280
	ds_read_b128 v[250:253], v211 offset:35104
	ds_read_b128 v[202:205], v211 offset:35616
	v_exp_f32_e32 v229, v229
	v_exp_f32_e32 v230, v230
	s_waitcnt lgkmcnt(3)
	v_mfma_f32_32x32x16_bf16 v[82:97], v[66:69], v[144:147], 0
	v_exp_f32_e32 v231, v231
	v_exp_f32_e32 v238, v238
	v_exp_f32_e32 v239, v239
	v_exp_f32_e32 v240, v240
	v_exp_f32_e32 v241, v241
	s_waitcnt lgkmcnt(2)
	v_mfma_f32_32x32x16_bf16 v[66:81], v[70:73], v[144:147], 0
	s_waitcnt lgkmcnt(1)
	v_mfma_f32_32x32x16_bf16 v[82:97], v[250:253], v[140:143], v[82:97]
	s_waitcnt lgkmcnt(0)
	v_mfma_f32_32x32x16_bf16 v[66:81], v[202:205], v[140:143], v[66:81]
	ds_read_b128 v[202:205], v211 offset:37440
	ds_read_b128 v[250:253], v211 offset:37952
	s_waitcnt lgkmcnt(1)
	v_mfma_f32_32x32x16_bf16 v[82:97], v[202:205], v[136:139], v[82:97]
	s_waitcnt lgkmcnt(0)
	v_mfma_f32_32x32x16_bf16 v[66:81], v[250:253], v[136:139], v[66:81]
	ds_read_b128 v[202:205], v211 offset:39776
	ds_read_b128 v[250:253], v211 offset:40288
	s_waitcnt lgkmcnt(1)
	v_mfma_f32_32x32x16_bf16 v[82:97], v[202:205], v[132:135], v[82:97]
	s_waitcnt lgkmcnt(0)
	v_mfma_f32_32x32x16_bf16 v[66:81], v[250:253], v[132:135], v[66:81]
	ds_read_b128 v[202:205], v211 offset:41984
	ds_read_b128 v[250:253], v211 offset:42496
	s_waitcnt lgkmcnt(1)
	v_mfma_f32_32x32x16_bf16 v[82:97], v[202:205], v[128:131], v[82:97]
	s_waitcnt lgkmcnt(0)
	v_mfma_f32_32x32x16_bf16 v[66:81], v[250:253], v[128:131], v[66:81]
	ds_read_b128 v[202:205], v211 offset:44320
	ds_read_b128 v[250:253], v211 offset:44832
	s_waitcnt lgkmcnt(1)
	v_mfma_f32_32x32x16_bf16 v[82:97], v[202:205], v[124:127], v[82:97]
	s_waitcnt lgkmcnt(0)
	v_mfma_f32_32x32x16_bf16 v[66:81], v[250:253], v[124:127], v[66:81]
	ds_read_b128 v[202:205], v211 offset:46656
	ds_read_b128 v[250:253], v211 offset:47168
	s_waitcnt lgkmcnt(1)
	v_mfma_f32_32x32x16_bf16 v[82:97], v[202:205], v[120:123], v[82:97]
	s_waitcnt lgkmcnt(0)
	v_mfma_f32_32x32x16_bf16 v[66:81], v[250:253], v[120:123], v[66:81]
	ds_read_b128 v[202:205], v211 offset:48992
	ds_read_b128 v[250:253], v211 offset:49504
	s_waitcnt lgkmcnt(1)
	v_mfma_f32_32x32x16_bf16 v[82:97], v[202:205], v[116:119], v[82:97]
	s_waitcnt lgkmcnt(0)
	v_mfma_f32_32x32x16_bf16 v[66:81], v[250:253], v[116:119], v[66:81]
	ds_read_b128 v[202:205], v215
	ds_read_b128 v[250:253], v215 offset:512
	s_waitcnt lgkmcnt(1)
	v_mfma_f32_32x32x16_bf16 v[82:97], v[202:205], v[112:115], v[82:97]
	s_waitcnt lgkmcnt(0)
	v_mfma_f32_32x32x16_bf16 v[66:81], v[250:253], v[112:115], v[66:81]
	ds_read_b128 v[202:205], v215 offset:2336
	ds_read_b128 v[250:253], v215 offset:2848
	s_waitcnt lgkmcnt(1)
	v_mfma_f32_32x32x16_bf16 v[82:97], v[202:205], v[108:111], v[82:97]
	s_waitcnt lgkmcnt(0)
	v_mfma_f32_32x32x16_bf16 v[66:81], v[250:253], v[108:111], v[66:81]
	ds_read_b128 v[202:205], v215 offset:4672
	ds_read_b128 v[250:253], v215 offset:5184
	s_waitcnt lgkmcnt(1)
	v_mfma_f32_32x32x16_bf16 v[82:97], v[202:205], v[104:107], v[82:97]
	s_waitcnt lgkmcnt(0)
	v_mfma_f32_32x32x16_bf16 v[66:81], v[250:253], v[104:107], v[66:81]
	ds_read_b128 v[202:205], v215 offset:7008
	ds_read_b128 v[250:253], v215 offset:7520
	s_waitcnt lgkmcnt(1)
	v_mfma_f32_32x32x16_bf16 v[82:97], v[202:205], v[100:103], v[82:97]
	v_exp_f32_e32 v202, v242
	v_exp_f32_e32 v242, v246
	v_exp_f32_e32 v246, v227
	v_add_f32_e32 v227, 0, v168
	v_add_f32_e32 v227, v183, v227
	v_add_f32_e32 v227, v169, v227
	v_add_f32_e32 v227, v182, v227
	v_add_f32_e32 v227, v170, v227
	v_add_f32_e32 v227, v181, v227
	v_add_f32_e32 v227, v171, v227
	v_add_f32_e32 v227, v180, v227
	v_add_f32_e32 v227, v172, v227
	v_add_f32_e32 v227, v179, v227
	v_add_f32_e32 v227, v173, v227
	v_add_f32_e32 v227, v178, v227
	v_add_f32_e32 v227, v174, v227
	v_exp_f32_e32 v203, v243
	v_add_f32_e32 v227, v177, v227
	v_exp_f32_e32 v204, v244
	v_add_f32_e32 v227, v175, v227
	v_exp_f32_e32 v205, v245
	v_add_f32_e32 v227, v176, v227
	v_add_f32_e32 v227, v202, v227
	v_add_f32_e32 v227, v203, v227
	v_add_f32_e32 v227, v204, v227
	v_add_f32_e32 v227, v205, v227
	v_add_f32_e32 v227, v242, v227
	v_add_f32_e32 v227, v229, v227
	v_add_f32_e32 v227, v230, v227
	v_add_f32_e32 v227, v231, v227
	v_exp_f32_e32 v243, v228
	v_add_f32_e32 v227, v238, v227
	v_exp_f32_e32 v244, v247
	v_add_f32_e32 v227, v239, v227
	s_waitcnt lgkmcnt(0)
	v_mfma_f32_32x32x16_bf16 v[66:81], v[250:253], v[100:103], v[66:81]
	v_exp_f32_e32 v245, v248
	v_add_f32_e32 v227, v240, v227
	v_add_f32_e32 v227, v241, v227
	v_add_f32_e32 v227, v243, v227
	v_add_f32_e32 v227, v244, v227
	v_add_f32_e32 v227, v245, v227
	v_add_f32_e32 v227, v246, v227
	v_mov_b32_e32 v228, v227
	v_cvt_pk_bf16_f32 v168, v168, v183
	v_cvt_pk_bf16_f32 v169, v169, v182
	v_cvt_pk_bf16_f32 v170, v170, v181
	v_cvt_pk_bf16_f32 v171, v171, v180
	v_cvt_pk_bf16_f32 v172, v172, v179
	v_cvt_pk_bf16_f32 v173, v173, v178
	v_cvt_pk_bf16_f32 v174, v174, v177
	v_cvt_pk_bf16_f32 v175, v175, v176
	v_cvt_pk_bf16_f32 v176, v202, v203
	v_cvt_pk_bf16_f32 v177, v204, v205
	v_cvt_pk_bf16_f32 v178, v242, v229
	v_cvt_pk_bf16_f32 v179, v230, v231
	v_cvt_pk_bf16_f32 v180, v238, v239
	v_cvt_pk_bf16_f32 v181, v240, v241
	v_cvt_pk_bf16_f32 v182, v243, v244
	v_cvt_pk_bf16_f32 v183, v245, v246
	s_nop 1
	v_permlane32_swap_b32_e32 v227, v228
	v_permlane32_swap_b32_e32 v168, v170
	v_permlane32_swap_b32_e32 v169, v171
	v_permlane32_swap_b32_e32 v172, v174
	v_permlane32_swap_b32_e32 v173, v175
	v_permlane32_swap_b32_e32 v176, v178
	v_permlane32_swap_b32_e32 v177, v179
	v_permlane32_swap_b32_e32 v180, v182
	v_permlane32_swap_b32_e32 v181, v183
	s_add_i32 s4, s0, 1
	s_cmp_lt_u32 s4, s25
	s_cselect_b64 s[20:21], -1, 0
	s_cmp_ge_u32 s4, s25
	s_cbranch_scc1 .LBB0_1394
	v_add_u32_e32 v156, 0x41, v225
	v_add_u32_e32 v158, 0x61, v225
	v_ashrrev_i32_e32 v157, 31, v156
	v_ashrrev_i32_e32 v159, 31, v158
	v_lshlrev_b64 v[148:149], 8, v[156:157]
	v_lshlrev_b64 v[150:151], 8, v[158:159]
	v_add_u32_e32 v164, 0x41, v226
	v_lshl_add_u64 v[148:149], v[190:191], 0, v[148:149]
	v_lshl_add_u64 v[152:153], v[190:191], 0, v[150:151]
	v_mad_i64_i32 v[156:157], s[4:5], v156, s1, v[192:193]
	v_mad_i64_i32 v[160:161], s[4:5], v158, s1, v[192:193]
	v_mad_i64_i32 v[164:165], s[4:5], v164, s1, v[194:195]
	global_load_dwordx4 v[148:151], v[148:149], off
	s_nop 0
	global_load_dwordx4 v[152:155], v[152:153], off
	s_nop 0
	global_load_dwordx4 v[156:159], v[156:157], off
	s_nop 0
	global_load_dwordx4 v[160:163], v[160:161], off
	s_nop 0
	global_load_dwordx4 v[164:167], v[164:165], off offset:256

.LBB0_1396:
	s_cmp_eq_u32 s100, 0
	s_cbranch_scc1 .Lblkb1_a
	s_barrier
	v_max_f32_e32 v168, v83, v83
	v_max_f32_e32 v169, v82, v82
	v_max_f32_e32 v168, v169, v168
	v_max3_f32 v168, v168, v84, v85
	v_max3_f32 v168, v168, v86, v87
	v_max3_f32 v168, v168, v88, v89
	v_max3_f32 v168, v168, v90, v91
	v_max3_f32 v168, v168, v92, v93
	v_max3_f32 v168, v168, v94, v95
	v_max3_f32 v168, v168, v96, v97
	v_max3_f32 v168, v168, v66, v67
	v_max3_f32 v168, v168, v68, v69
	v_max3_f32 v168, v168, v70, v71
	v_max3_f32 v168, v168, v72, v73
	v_max3_f32 v168, v168, v74, v75
	v_max3_f32 v168, v168, v76, v77
	v_max3_f32 v168, v168, v78, v79
	v_max3_f32 v168, v168, v80, v81
	v_mov_b32_e32 v169, v168
	s_nop 1
	v_permlane32_swap_b32_e32 v168, v169
	v_max_f32_e32 v169, v169, v169
	v_max_f32_e32 v168, v168, v168
	v_max_f32_e32 v168, v168, v169
	v_sub_f32_e32 v169, v168, v224
	v_mul_f32_e32 v169, 0x3d93cd3a, v169
	v_cmp_ge_f32_e32 vcc, s2, v169
	s_cmp_eq_u64 vcc, exec
	s_cselect_b64 s[40:41], -1, 0
	s_andn2_b64 vcc, exec, s[20:21]
	s_branch .Lblkb1_j

.Lblkb1_j:
	s_cbranch_vccnz .LBB0_1398
	s_waitcnt vmcnt(0)
	s_waitcnt vmcnt(4)
	ds_write_b128 v212, v[148:151] offset:16384
	s_waitcnt vmcnt(3)
	ds_write_b128 v213, v[152:155] offset:16384
	s_waitcnt vmcnt(2)
	ds_write_b128 v196, v[156:159] offset:51200
	s_waitcnt vmcnt(1)
	ds_write_b128 v197, v[160:163] offset:51200
	s_waitcnt vmcnt(0)
	ds_write_b128 v219, v[164:167]

.LBB0_1402:
	s_cmp_eq_u32 s100, 0
	s_cbranch_scc1 .Lblk1_a
	s_waitcnt lgkmcnt(0)
	s_barrier
	v_cndmask_b32_e64 v176, v148, v224, s[40:41]
	v_mul_f32_e32 v150, 0xbdd53b94, v176
	v_mov_b32_e32 v151, v150
	v_fmamk_f32 v82, v82, 0x3dd53b94, v150
	v_fmamk_f32 v83, v83, 0x3dd53b94, v150
	v_fmamk_f32 v84, v84, 0x3dd53b94, v150
	v_fmamk_f32 v85, v85, 0x3dd53b94, v150
	v_fmamk_f32 v86, v86, 0x3dd53b94, v150
	v_fmamk_f32 v87, v87, 0x3dd53b94, v150
	v_fmamk_f32 v88, v88, 0x3dd53b94, v150
	v_fmamk_f32 v89, v89, 0x3dd53b94, v150
	v_fmamk_f32 v90, v90, 0x3dd53b94, v150
	v_fmamk_f32 v91, v91, 0x3dd53b94, v150
	v_fmamk_f32 v92, v92, 0x3dd53b94, v150
	v_fmamk_f32 v93, v93, 0x3dd53b94, v150
	v_fmamk_f32 v94, v94, 0x3dd53b94, v150
	v_fmamk_f32 v95, v95, 0x3dd53b94, v150
	v_fmamk_f32 v96, v96, 0x3dd53b94, v150
	v_fmac_f32_e32 v151, 0x3dd53b94, v97
	v_exp_f32_e32 v168, v82
	v_exp_f32_e32 v181, v83
	v_exp_f32_e32 v169, v84
	v_exp_f32_e32 v180, v85
	v_exp_f32_e32 v170, v86
	v_exp_f32_e32 v179, v87
	v_exp_f32_e32 v171, v88
	v_exp_f32_e32 v178, v89
	v_exp_f32_e32 v172, v90
	v_exp_f32_e32 v177, v91
	v_exp_f32_e32 v173, v92
	v_exp_f32_e32 v175, v93
	v_exp_f32_e32 v166, v94
	v_exp_f32_e32 v174, v95
	v_exp_f32_e32 v165, v96
	v_exp_f32_e32 v167, v151
	v_pk_fma_f32 v[160:161], v[66:67], s[34:35], v[150:151] op_sel_hi:[1,0,0]
	v_add_f32_e32 v66, v221, v222
	v_fmac_f32_e32 v66, v217, v210
	v_add_f32_e32 v210, v227, v228
	s_addk_i32 s26, 0x80
	s_add_i32 s0, s0, 2
	v_pk_fma_f32 v[158:159], v[68:69], s[34:35], v[150:151] op_sel_hi:[1,0,0]
	v_pk_fma_f32 v[154:155], v[70:71], s[34:35], v[150:151] op_sel_hi:[1,0,0]
	v_pk_fma_f32 v[152:153], v[72:73], s[34:35], v[150:151] op_sel_hi:[1,0,0]
	v_pk_fma_f32 v[148:149], v[74:75], s[34:35], v[150:151] op_sel_hi:[1,0,0]
	v_pk_fma_f32 v[162:163], v[76:77], s[34:35], v[150:151] op_sel_hi:[1,0,0]
	v_pk_fma_f32 v[156:157], v[78:79], s[34:35], v[150:151] op_sel_hi:[1,0,0]
	v_pk_fma_f32 v[150:151], v[80:81], s[34:35], v[150:151] op_sel_hi:[1,0,0]
	v_fmac_f32_e32 v210, v66, v223
	s_cmp_lt_u32 s0, s25
	v_add_u32_e32 v189, 0xffffff80, v189
	s_branch .Lblk1_j

.Lblk1_j:
	s_cbranch_scc0 .LBB0_1404
	v_mov_b32_e32 v217, v164
	s_branch .LBB0_1386

	.amdhsa_kernel _ZN2mk6mk_fwdENS_4ArgsE
		.amdhsa_group_segment_fixed_size 0
		.amdhsa_private_segment_fixed_size 0
		.amdhsa_kernarg_size 472
		.amdhsa_user_sgpr_count 2
		.amdhsa_user_sgpr_dispatch_ptr 0
		.amdhsa_user_sgpr_queue_ptr 0
		.amdhsa_user_sgpr_kernarg_segment_ptr 1
		.amdhsa_user_sgpr_dispatch_id 0
		.amdhsa_user_sgpr_kernarg_preload_length 0
		.amdhsa_user_sgpr_kernarg_preload_offset 0
		.amdhsa_user_sgpr_private_segment_size 0
		.amdhsa_uses_dynamic_stack 0
		.amdhsa_enable_private_segment 0
		.amdhsa_system_sgpr_workgroup_id_x 1
		.amdhsa_system_sgpr_workgroup_id_y 0
		.amdhsa_system_sgpr_workgroup_id_z 0
		.amdhsa_system_sgpr_workgroup_info 0
		.amdhsa_system_vgpr_workitem_id 0
		.amdhsa_next_free_vgpr 256
		.amdhsa_next_free_sgpr 102
		.amdhsa_accum_offset 256
		.amdhsa_reserve_vcc 1
		.amdhsa_float_round_mode_32 0
		.amdhsa_float_round_mode_16_64 0
		.amdhsa_float_denorm_mode_32 3
		.amdhsa_float_denorm_mode_16_64 3
		.amdhsa_dx10_clamp 1
		.amdhsa_ieee_mode 1
		.amdhsa_fp16_overflow 0
		.amdhsa_tg_split 0
		.amdhsa_exception_fp_ieee_invalid_op 0
		.amdhsa_exception_fp_denorm_src 0
		.amdhsa_exception_fp_ieee_div_zero 0
		.amdhsa_exception_fp_ieee_overflow 0
		.amdhsa_exception_fp_ieee_underflow 0
		.amdhsa_exception_fp_ieee_inexact 0
		.amdhsa_exception_int_div_zero 0
	.end_amdhsa_kernel

amdhsa.kernels:
  - .agpr_count:     0
    .args:
      - .offset:         0
        .size:           216
        .value_kind:     by_value
      - .offset:         216
        .size:           4
        .value_kind:     hidden_block_count_x
      - .offset:         220
        .size:           4
        .value_kind:     hidden_block_count_y
      - .offset:         224
        .size:           4
        .value_kind:     hidden_block_count_z
      - .offset:         228
        .size:           2
        .value_kind:     hidden_group_size_x
      - .offset:         230
        .size:           2
        .value_kind:     hidden_group_size_y
      - .offset:         232
        .size:           2
        .value_kind:     hidden_group_size_z
      - .offset:         234
        .size:           2
        .value_kind:     hidden_remainder_x
      - .offset:         236
        .size:           2
        .value_kind:     hidden_remainder_y
      - .offset:         238
        .size:           2
        .value_kind:     hidden_remainder_z
      - .offset:         256
        .size:           8
        .value_kind:     hidden_global_offset_x
      - .offset:         264
        .size:           8
        .value_kind:     hidden_global_offset_y
      - .offset:         272
        .size:           8
        .value_kind:     hidden_global_offset_z
      - .offset:         280
        .size:           2
        .value_kind:     hidden_grid_dims
      - .offset:         336
        .size:           4
        .value_kind:     hidden_dynamic_lds_size
    .group_segment_fixed_size: 0
    .kernarg_segment_align: 8
    .kernarg_segment_size: 472
    .language:       OpenCL C
    .language_version:
      - 2
      - 0
    .max_flat_workgroup_size: 512
    .name:           _ZN2mk6mk_fwdENS_4ArgsE
    .private_segment_fixed_size: 0
    .sgpr_count:     108
    .sgpr_spill_count: 129
    .symbol:         _ZN2mk6mk_fwdENS_4ArgsE.kd
    .uniform_work_group_size: 1
    .uses_dynamic_stack: false
    .vgpr_count:     256
    .vgpr_spill_count: 0
    .wavefront_size: 64
